# v110 + norm phases: next iteration's 16 x-row loads prefetched one iteration ahead into a shadow set (14 VGPR quads + 2 LDS-DMA chunks)
# speedup vs baseline: 1.0039x; 1.0039x over previous
.LBB0_439:
	s_cmp_gt_i32 s47, 3
	s_mov_b64 s[2:3], -1
	s_cbranch_scc0 .LBB0_482
	v_ashrrev_i32_e32 v0, 6, v166
	v_readlane_b32 s2, v252, 17
	s_nop 1
	v_add_u32_e32 v66, s2, v0
	v_cmp_gt_i32_e32 vcc, s4, v66
	s_and_saveexec_b64 s[2:3], vcc
	s_cbranch_execz .LBB0_481
	v_and_b32_e32 v3, 64, v220
	v_add_u32_e32 v3, 64, v3
	v_xor_b32_e32 v5, 32, v220
	v_cmp_lt_i32_e32 vcc, v5, v3
	s_load_dword s12, s[96:97], 0x0
	v_lshlrev_b32_e32 v0, 2, v166
	v_cndmask_b32_e32 v5, v220, v5, vcc
	v_lshlrev_b32_e32 v108, 2, v5
	v_xor_b32_e32 v5, 16, v220
	v_cmp_lt_i32_e32 vcc, v5, v3
	v_and_b32_e32 v2, 0xfc, v0
	s_waitcnt lgkmcnt(0)
	s_lshl_b32 s5, s12, 3
	v_cndmask_b32_e32 v5, v220, v5, vcc
	v_lshlrev_b32_e32 v109, 2, v5
	v_xor_b32_e32 v5, 8, v220
	v_cmp_lt_i32_e32 vcc, v5, v3
	s_add_u32 s8, s44, 0x32000
	v_or_b32_e32 v4, 0x100, v2
	v_cndmask_b32_e32 v5, v220, v5, vcc
	s_addc_u32 s9, s45, 0
	v_readlane_b32 s6, v254, 57
	v_lshlrev_b32_e32 v6, 2, v4
	v_mov_b32_e32 v7, v1
	v_lshlrev_b32_e32 v110, 2, v5
	v_xor_b32_e32 v5, 4, v220
	v_readlane_b32 s7, v254, 58
	s_lshl_b32 s6, s6, 10
	v_lshl_add_u64 v[70:71], s[8:9], 0, v[6:7]
	v_or_b32_e32 v6, 0x200, v2
	v_cmp_lt_i32_e32 vcc, v5, v3
	s_ashr_i32 s7, s6, 31
	v_lshlrev_b32_e32 v8, 2, v6
	v_mov_b32_e32 v9, v1
	v_cndmask_b32_e32 v5, v220, v5, vcc
	s_lshl_b64 s[6:7], s[6:7], 2
	v_lshl_add_u64 v[72:73], s[8:9], 0, v[8:9]
	v_or_b32_e32 v8, 0x300, v2
	v_lshlrev_b32_e32 v111, 2, v5
	v_xor_b32_e32 v5, 2, v220
	s_add_u32 s10, s86, s6
	v_lshlrev_b32_e32 v0, 2, v2
	v_lshlrev_b32_e32 v10, 2, v8
	v_mov_b32_e32 v11, v1
	v_cmp_lt_i32_e32 vcc, v5, v3
	s_addc_u32 s11, s87, s7
	s_add_i32 s6, s4, -1
	v_lshl_add_u64 v[68:69], s[8:9], 0, v[0:1]
	v_lshl_add_u64 v[74:75], s[8:9], 0, v[10:11]
	v_cndmask_b32_e32 v5, v220, v5, vcc
	v_readlane_b32 s8, v253, 39
	s_add_u32 s22, s44, 0x3000
	v_lshlrev_b32_e32 v112, 2, v5
	v_xor_b32_e32 v5, 1, v220
	v_lshl_add_u64 v[76:77], s[10:11], 0, v[0:1]
	v_lshl_add_u64 v[78:79], s[54:55], 0, v[0:1]
	v_lshlrev_b32_e32 v0, 1, v2
	v_readlane_b32 s9, v253, 40
	v_ashrrev_i32_e32 v67, 31, v66
	s_addc_u32 s23, s45, 0
	s_lshl_b32 s24, s12, 5
	v_cmp_lt_i32_e32 vcc, v5, v3
	v_lshl_add_u64 v[80:81], s[8:9], 0, v[0:1]
	v_lshlrev_b64 v[10:11], 11, v[66:67]
	v_and_b32_e32 v0, 63, v166
	v_cndmask_b32_e32 v3, v220, v5, vcc
	v_lshl_or_b32 v10, v0, 3, v10
	s_ashr_i32 s25, s24, 31
	v_lshlrev_b32_e32 v113, 2, v3
	v_lshl_add_u64 v[82:83], s[8:9], 0, v[10:11]
	s_lshl_b64 s[30:31], s[24:25], 11
	s_lshl_b32 s7, s12, 4
	s_mul_i32 s8, s12, 24
	v_readlane_b32 s12, v254, 54
	s_mov_b64 s[34:35], 0
	v_lshlrev_b32_e32 v84, 2, v2
	v_lshlrev_b32_e32 v86, 2, v4
	v_lshlrev_b32_e32 v88, 2, v6
	v_lshlrev_b32_e32 v90, 2, v8
	v_and_b32_e32 v223, 63, v166
	v_lshlrev_b32_e32 v223, 4, v223
	v_add_u32_e32 v248, 0x12000, v223
	v_mov_b32_e32 v242, 0x2000000
	v_mov_b32_e32 v243, 0
	v_lshrrev_b32_e32 v249, 6, v166
	v_lshlrev_b32_e32 v249, 11, v249
	v_add_u32_e32 v249, v249, v223
	v_add_u32_e32 v249, 0x13000, v249
	v_lshlrev_b32_e32 v50, 4, v166
	s_mov_b64 s[98:99], s[22:23]
	global_load_dwordx4 v[10:13], v50, s[98:99]
	s_add_u32 s98, s98, 0x6000
	s_addc_u32 s99, s99, 0
	global_load_dwordx4 v[14:17], v50, s[98:99]
	s_add_u32 s98, s98, 0x6000
	s_addc_u32 s99, s99, 0
	global_load_dwordx4 v[18:21], v50, s[98:99]
	s_add_u32 s98, s98, 0x6000
	s_addc_u32 s99, s99, 0
	global_load_dwordx4 v[22:25], v50, s[98:99]
	s_add_u32 s98, s98, 0x6000
	s_addc_u32 s99, s99, 0
	global_load_dwordx4 v[26:29], v50, s[98:99]
	s_add_u32 s98, s98, 0x6000
	s_addc_u32 s99, s99, 0
	global_load_dwordx4 v[30:33], v50, s[98:99]
	s_add_u32 s98, s98, 0x6000
	s_addc_u32 s99, s99, 0
	global_load_dwordx4 v[34:37], v50, s[98:99]
	s_add_u32 s98, s98, 0x6000
	s_addc_u32 s99, s99, 0
	global_load_dwordx4 v[38:41], v50, s[98:99]
	s_add_u32 s98, s98, 0x6000
	s_addc_u32 s99, s99, 0
	global_load_dwordx4 v[42:45], v50, s[98:99]
	s_add_u32 s98, s98, 0x6000
	s_addc_u32 s99, s99, 0
	v_lshrrev_b32_e32 v54, 6, v166
	v_lshlrev_b32_e32 v54, 10, v54
	v_mov_b32_e32 v55, 0
	v_lshl_add_u64 v[52:53], v[76:77], 0, v[54:55]
	v_add_u32_e32 v51, 0x12000, v50
	v_cmp_gt_u32_e32 vcc, 0x100, v166
	s_and_saveexec_b64 s[98:99], vcc
	global_load_dwordx4 v[46:49], v[52:53], off
	s_waitcnt vmcnt(0)
	ds_write_b128 v51, v[46:49]
	s_mov_b64 exec, s[98:99]
	ds_write_b128 v50, v[10:13]
	v_add_u32_e32 v50, 0x2000, v50
	ds_write_b128 v50, v[14:17]
	v_add_u32_e32 v50, 0x2000, v50
	ds_write_b128 v50, v[18:21]
	v_add_u32_e32 v50, 0x2000, v50
	ds_write_b128 v50, v[22:25]
	v_add_u32_e32 v50, 0x2000, v50
	ds_write_b128 v50, v[26:29]
	v_add_u32_e32 v50, 0x2000, v50
	ds_write_b128 v50, v[30:33]
	v_add_u32_e32 v50, 0x2000, v50
	ds_write_b128 v50, v[34:37]
	v_add_u32_e32 v50, 0x2000, v50
	ds_write_b128 v50, v[38:41]
	v_add_u32_e32 v50, 0x2000, v50
	ds_write_b128 v50, v[42:45]
	s_waitcnt lgkmcnt(0)
	s_barrier
	s_branch .LBB0_443

.LBB0_443:
	v_readlane_b32 s56, v254, 4
	v_min_i32_e32 v6, s6, v66
	v_readlane_b32 s71, v254, 19
	v_add_u32_e32 v0, 0xffff8000, v6
	v_ashrrev_i32_e32 v2, 31, v6
	v_cmp_gt_i32_e32 vcc, s40, v6
	v_mov_b32_e32 v4, s55
	v_readlane_b32 s70, v254, 18
	v_mov_b32_e32 v5, s71
	v_cndmask_b32_e32 v3, 0, v2, vcc
	v_cndmask_b32_e32 v2, v0, v6, vcc
	v_cndmask_b32_e32 v5, v4, v5, vcc
	v_mov_b32_e32 v4, s54
	v_mov_b32_e32 v7, s70
	v_cndmask_b32_e32 v4, v4, v7, vcc
	v_lshlrev_b64 v[2:3], 12, v[2:3]
	v_lshl_add_u64 v[2:3], v[4:5], 0, v[2:3]
	v_mov_b32_e32 v85, v1
	v_lshl_add_u64 v[2:3], v[2:3], 0, v[84:85]
	v_lshl_add_u64 v[212:213], v[2:3], 0, v[242:243]
	v_readfirstlane_b32 s98, v66
	s_sub_i32 s99, s98, 0x2000
	s_cmp_lt_u32 s99, 0x4800
	s_cbranch_scc0 .Lnp_1_0_ld
	s_waitcnt vmcnt(0)
	v_mov_b64_e32 v[62:63], v[122:123]
	v_mov_b64_e32 v[64:65], v[124:125]
	v_mov_b64_e32 v[50:51], v[126:127]
	v_mov_b64_e32 v[52:53], v[128:129]
	v_mov_b64_e32 v[46:47], v[130:131]
	v_mov_b64_e32 v[48:49], v[132:133]
	v_mov_b64_e32 v[30:31], v[134:135]
	v_mov_b64_e32 v[32:33], v[136:137]
	s_branch .Lnp_1_0_pf
.Lnp_1_0_ld:
	global_load_dwordx4 v[62:65], v[2:3], off nt
	global_load_dwordx4 v[50:53], v[2:3], off offset:1024 nt
	global_load_dwordx4 v[46:49], v[2:3], off offset:2048 nt
	global_load_dwordx4 v[30:33], v[2:3], off offset:3072 nt
.Lnp_1_0_pf:
	s_cmp_lt_u32 s98, 0x4800
	s_cbranch_scc0 .Lnp_1_0_dn
	global_load_dwordx4 v[122:125], v[212:213], off nt
	global_load_dwordx4 v[126:129], v[212:213], off offset:1024 nt
	global_load_dwordx4 v[130:133], v[212:213], off offset:2048 nt
	global_load_dwordx4 v[134:137], v[212:213], off offset:3072 nt
.Lnp_1_0_dn:
	v_cmp_lt_i32_e32 vcc, s14, v6
	v_readlane_b32 s57, v254, 5
	v_readlane_b32 s58, v254, 6
	v_readlane_b32 s59, v254, 7
	v_readlane_b32 s60, v254, 8
	v_readlane_b32 s61, v254, 9
	v_readlane_b32 s62, v254, 10
	v_readlane_b32 s63, v254, 11
	v_readlane_b32 s64, v254, 12
	v_readlane_b32 s65, v254, 13
	v_readlane_b32 s66, v254, 14
	v_readlane_b32 s67, v254, 15
	v_readlane_b32 s68, v254, 16
	v_readlane_b32 s69, v254, 17
	s_and_saveexec_b64 s[36:37], vcc
	s_cbranch_execz .LBB0_445
	v_readlane_b32 s10, v253, 18
	v_lshlrev_b64 v[2:3], 12, v[0:1]
	v_readlane_b32 s11, v253, 19
	v_mov_b32_e32 v87, v1
	v_mov_b32_e32 v89, v1
	v_lshl_add_u64 v[10:11], s[10:11], 0, v[2:3]
	s_mov_b64 s[10:11], 0x800000
	v_lshl_add_u64 v[8:9], v[10:11], 0, s[10:11]
	s_mov_b64 s[10:11], 0x1000000
	v_lshl_add_u64 v[6:7], v[10:11], 0, s[10:11]
	s_mov_b64 s[10:11], 0x1800000
	v_lshl_add_u64 v[4:5], v[10:11], 0, s[10:11]
	v_lshl_add_u64 v[10:11], v[10:11], 0, v[84:85]
	v_lshl_add_u64 v[8:9], v[8:9], 0, v[84:85]
	v_lshl_add_u64 v[6:7], v[6:7], 0, v[84:85]
	v_lshl_add_u64 v[4:5], v[4:5], 0, v[84:85]
	v_mov_b32_e32 v91, v1
	v_lshl_add_u64 v[2:3], v[78:79], 0, v[2:3]
	global_load_dwordx4 v[114:117], v[10:11], off
	global_load_dwordx4 v[118:121], v[8:9], off
	global_load_dwordx4 v[122:125], v[6:7], off
	global_load_dwordx4 v[126:129], v[4:5], off
	global_load_dwordx4 v[200:203], v[68:69], off
	global_load_dwordx4 v[130:133], v[10:11], off offset:1024
	global_load_dwordx4 v[134:137], v[8:9], off offset:1024
	global_load_dwordx4 v[138:141], v[6:7], off offset:1024
	global_load_dwordx4 v[142:145], v[4:5], off offset:1024
	global_load_dwordx4 v[204:207], v[70:71], off
	global_load_dwordx4 v[146:149], v[10:11], off offset:2048
	global_load_dwordx4 v[150:153], v[8:9], off offset:2048
	global_load_dwordx4 v[176:179], v[6:7], off offset:2048
	global_load_dwordx4 v[180:183], v[4:5], off offset:2048
	global_load_dwordx4 v[208:211], v[72:73], off
	global_load_dwordx4 v[184:187], v[10:11], off offset:3072
	global_load_dwordx4 v[188:191], v[8:9], off offset:3072
	global_load_dwordx4 v[192:195], v[6:7], off offset:3072
	global_load_dwordx4 v[196:199], v[4:5], off offset:3072
	global_load_dwordx4 v[20:23], v[74:75], off
	s_waitcnt vmcnt(15)
	v_pk_add_f32 v[114:115], v[114:115], v[118:119]
	v_pk_add_f32 v[116:117], v[116:117], v[120:121]
	v_pk_add_f32 v[114:115], v[114:115], v[122:123]
	v_pk_add_f32 v[116:117], v[116:117], v[124:125]
	v_pk_add_f32 v[114:115], v[114:115], v[126:127]
	v_pk_add_f32 v[116:117], v[116:117], v[128:129]
	v_pk_fma_f32 v[62:63], v[114:115], v[200:201], v[62:63]
	v_pk_fma_f32 v[64:65], v[116:117], v[202:203], v[64:65]
	global_store_dwordx4 v[2:3], v[62:65], off
	s_waitcnt vmcnt(11)
	v_pk_add_f32 v[130:131], v[130:131], v[134:135]
	v_pk_add_f32 v[132:133], v[132:133], v[136:137]
	v_pk_add_f32 v[130:131], v[130:131], v[138:139]
	v_pk_add_f32 v[132:133], v[132:133], v[140:141]
	v_pk_add_f32 v[130:131], v[130:131], v[142:143]
	v_pk_add_f32 v[132:133], v[132:133], v[144:145]
	v_pk_fma_f32 v[50:51], v[130:131], v[204:205], v[50:51]
	v_pk_fma_f32 v[52:53], v[132:133], v[206:207], v[52:53]
	global_store_dwordx4 v[2:3], v[50:53], off offset:1024
	s_waitcnt vmcnt(7)
	v_pk_add_f32 v[146:147], v[146:147], v[150:151]
	v_pk_add_f32 v[148:149], v[148:149], v[152:153]
	v_pk_add_f32 v[146:147], v[146:147], v[176:177]
	v_pk_add_f32 v[148:149], v[148:149], v[178:179]
	v_pk_add_f32 v[146:147], v[146:147], v[180:181]
	v_pk_add_f32 v[148:149], v[148:149], v[182:183]
	v_pk_fma_f32 v[46:47], v[146:147], v[208:209], v[46:47]
	v_pk_fma_f32 v[48:49], v[148:149], v[210:211], v[48:49]
	global_store_dwordx4 v[2:3], v[46:49], off offset:2048
	s_waitcnt vmcnt(3)
	v_pk_add_f32 v[184:185], v[184:185], v[188:189]
	v_pk_add_f32 v[186:187], v[186:187], v[190:191]
	v_pk_add_f32 v[184:185], v[184:185], v[192:193]
	v_pk_add_f32 v[186:187], v[186:187], v[194:195]
	v_pk_add_f32 v[184:185], v[184:185], v[196:197]
	v_pk_add_f32 v[186:187], v[186:187], v[198:199]
	v_pk_fma_f32 v[30:31], v[184:185], v[20:21], v[30:31]
	v_pk_fma_f32 v[32:33], v[186:187], v[22:23], v[32:33]
	global_store_dwordx4 v[2:3], v[30:33], off offset:3072
.LBB0_445:
	s_or_b64 exec, exec, s[36:37]
	v_add_u32_e32 v96, s5, v66
	v_readlane_b32 s56, v254, 4
	v_min_i32_e32 v6, s6, v96
	v_readlane_b32 s71, v254, 19
	v_ashrrev_i32_e32 v2, 31, v6
	v_add_u32_e32 v0, 0xffff8000, v6
	v_cmp_gt_i32_e32 vcc, s40, v6
	v_mov_b32_e32 v4, s55
	v_readlane_b32 s70, v254, 18
	v_mov_b32_e32 v5, s71
	v_cndmask_b32_e32 v3, 0, v2, vcc
	v_cndmask_b32_e32 v2, v0, v6, vcc
	v_cndmask_b32_e32 v5, v4, v5, vcc
	v_mov_b32_e32 v4, s54
	v_mov_b32_e32 v7, s70
	v_cndmask_b32_e32 v4, v4, v7, vcc
	v_lshlrev_b64 v[2:3], 12, v[2:3]
	v_lshl_add_u64 v[2:3], v[4:5], 0, v[2:3]
	v_lshl_add_u64 v[2:3], v[2:3], 0, v[84:85]
	v_lshl_add_u64 v[212:213], v[2:3], 0, v[242:243]
	v_readfirstlane_b32 s98, v66
	s_sub_i32 s99, s98, 0x2000
	s_cmp_lt_u32 s99, 0x4800
	s_cbranch_scc0 .Lnp_1_1_ld
	v_mov_b64_e32 v[58:59], v[138:139]
	v_mov_b64_e32 v[60:61], v[140:141]
	v_mov_b64_e32 v[42:43], v[142:143]
	v_mov_b64_e32 v[44:45], v[144:145]
	v_mov_b64_e32 v[38:39], v[146:147]
	v_mov_b64_e32 v[40:41], v[148:149]
	v_mov_b64_e32 v[34:35], v[150:151]
	v_mov_b64_e32 v[36:37], v[152:153]
	s_branch .Lnp_1_1_pf
.Lnp_1_1_ld:
	global_load_dwordx4 v[58:61], v[2:3], off nt
	global_load_dwordx4 v[42:45], v[2:3], off offset:1024 nt
	global_load_dwordx4 v[38:41], v[2:3], off offset:2048 nt
	global_load_dwordx4 v[34:37], v[2:3], off offset:3072 nt
.Lnp_1_1_pf:
	s_cmp_lt_u32 s98, 0x4800
	s_cbranch_scc0 .Lnp_1_1_dn
	global_load_dwordx4 v[138:141], v[212:213], off nt
	global_load_dwordx4 v[142:145], v[212:213], off offset:1024 nt
	global_load_dwordx4 v[146:149], v[212:213], off offset:2048 nt
	global_load_dwordx4 v[150:153], v[212:213], off offset:3072 nt
.Lnp_1_1_dn:
	v_cmp_lt_i32_e32 vcc, s14, v6
	v_cmp_gt_i32_e64 s[10:11], s4, v96
	s_and_b64 vcc, vcc, s[10:11]
	v_readlane_b32 s57, v254, 5
	v_readlane_b32 s58, v254, 6
	v_readlane_b32 s59, v254, 7
	v_readlane_b32 s60, v254, 8
	v_readlane_b32 s61, v254, 9
	v_readlane_b32 s62, v254, 10
	v_readlane_b32 s63, v254, 11
	v_readlane_b32 s64, v254, 12
	v_readlane_b32 s65, v254, 13
	v_readlane_b32 s66, v254, 14
	v_readlane_b32 s67, v254, 15
	v_readlane_b32 s68, v254, 16
	v_readlane_b32 s69, v254, 17
	s_and_saveexec_b64 s[36:37], vcc
	s_cbranch_execz .LBB0_455
	v_readlane_b32 s10, v253, 18
	v_lshlrev_b64 v[2:3], 12, v[0:1]
	v_readlane_b32 s11, v253, 19
	v_mov_b32_e32 v85, v1
	v_cmp_gt_i32_e32 vcc, s4, v96
	v_lshl_add_u64 v[10:11], s[10:11], 0, v[2:3]
	s_mov_b64 s[10:11], 0x800000
	v_lshl_add_u64 v[8:9], v[10:11], 0, s[10:11]
	s_mov_b64 s[10:11], 0x1000000
	v_lshl_add_u64 v[6:7], v[10:11], 0, s[10:11]
	s_mov_b64 s[10:11], 0x1800000
	v_lshl_add_u64 v[4:5], v[10:11], 0, s[10:11]
	v_lshl_add_u64 v[10:11], v[10:11], 0, v[84:85]
	v_lshl_add_u64 v[16:17], v[8:9], 0, v[84:85]
	global_load_dwordx4 v[12:15], v[10:11], off
	v_lshl_add_u64 v[2:3], s[54:55], 0, v[2:3]
	global_load_dwordx4 v[16:19], v[16:17], off
	s_waitcnt vmcnt(0)
	v_pk_add_f32 v[16:17], v[12:13], v[16:17]
	v_lshl_add_u64 v[12:13], v[6:7], 0, v[84:85]
	v_pk_add_f32 v[18:19], v[14:15], v[18:19]
	global_load_dwordx4 v[12:15], v[12:13], off
	s_waitcnt vmcnt(0)
	v_pk_add_f32 v[16:17], v[16:17], v[12:13]
	v_lshl_add_u64 v[12:13], v[4:5], 0, v[84:85]
	v_pk_add_f32 v[18:19], v[18:19], v[14:15]
	global_load_dwordx4 v[12:15], v[12:13], off
	s_waitcnt vmcnt(0)
	v_pk_add_f32 v[18:19], v[18:19], v[14:15]
	v_pk_add_f32 v[16:17], v[16:17], v[12:13]
	global_load_dwordx4 v[12:15], v[68:69], off
	s_waitcnt vmcnt(0)
	v_pk_fma_f32 v[60:61], v[18:19], v[14:15], v[60:61]
	v_pk_fma_f32 v[58:59], v[16:17], v[12:13], v[58:59]
	s_and_saveexec_b64 s[38:39], vcc
	s_cbranch_execz .LBB0_448
	v_lshl_add_u64 v[12:13], v[2:3], 0, v[84:85]
	global_store_dwordx4 v[12:13], v[58:61], off

.LBB0_455:
	s_or_b64 exec, exec, s[36:37]
	v_add_u32_e32 v94, s7, v66
	v_readlane_b32 s56, v254, 4
	v_min_i32_e32 v6, s6, v94
	v_readlane_b32 s71, v254, 19
	v_ashrrev_i32_e32 v2, 31, v6
	v_add_u32_e32 v0, 0xffff8000, v6
	v_cmp_gt_i32_e32 vcc, s40, v6
	v_mov_b32_e32 v4, s55
	v_readlane_b32 s70, v254, 18
	v_mov_b32_e32 v5, s71
	v_cndmask_b32_e32 v3, 0, v2, vcc
	v_cndmask_b32_e32 v2, v0, v6, vcc
	v_cndmask_b32_e32 v5, v4, v5, vcc
	v_mov_b32_e32 v4, s54
	v_mov_b32_e32 v7, s70
	v_cndmask_b32_e32 v4, v4, v7, vcc
	v_lshlrev_b64 v[2:3], 12, v[2:3]
	v_lshl_add_u64 v[2:3], v[4:5], 0, v[2:3]
	v_mov_b32_e32 v85, v1
	v_lshl_add_u64 v[2:3], v[2:3], 0, v[84:85]
	v_lshl_add_u64 v[212:213], v[2:3], 0, v[242:243]
	v_readfirstlane_b32 s98, v66
	s_sub_i32 s99, s98, 0x2000
	s_cmp_lt_u32 s99, 0x4800
	s_cbranch_scc0 .Lnp_1_2_ld
	v_mov_b64_e32 v[54:55], v[204:205]
	v_mov_b64_e32 v[56:57], v[206:207]
	v_mov_b64_e32 v[26:27], v[208:209]
	v_mov_b64_e32 v[28:29], v[210:211]
	v_mov_b64_e32 v[18:19], v[224:225]
	v_mov_b64_e32 v[20:21], v[226:227]
	v_mov_b64_e32 v[14:15], v[234:235]
	v_mov_b64_e32 v[16:17], v[236:237]
	s_branch .Lnp_1_2_pf
.Lnp_1_2_ld:
	global_load_dwordx4 v[54:57], v[2:3], off nt
	global_load_dwordx4 v[26:29], v[2:3], off offset:1024 nt
	global_load_dwordx4 v[18:21], v[2:3], off offset:2048 nt
	global_load_dwordx4 v[14:17], v[2:3], off offset:3072 nt
.Lnp_1_2_pf:
	s_cmp_lt_u32 s98, 0x4800
	s_cbranch_scc0 .Lnp_1_2_dn
	global_load_dwordx4 v[204:207], v[212:213], off nt
	global_load_dwordx4 v[208:211], v[212:213], off offset:1024 nt
	global_load_dwordx4 v[224:227], v[212:213], off offset:2048 nt
	global_load_dwordx4 v[234:237], v[212:213], off offset:3072 nt
.Lnp_1_2_dn:
	v_cmp_lt_i32_e32 vcc, s14, v6
	v_cmp_gt_i32_e64 s[10:11], s4, v94
	s_and_b64 vcc, vcc, s[10:11]
	v_readlane_b32 s57, v254, 5
	v_readlane_b32 s58, v254, 6
	v_readlane_b32 s59, v254, 7
	v_readlane_b32 s60, v254, 8
	v_readlane_b32 s61, v254, 9
	v_readlane_b32 s62, v254, 10
	v_readlane_b32 s63, v254, 11
	v_readlane_b32 s64, v254, 12
	v_readlane_b32 s65, v254, 13
	v_readlane_b32 s66, v254, 14
	v_readlane_b32 s67, v254, 15
	v_readlane_b32 s68, v254, 16
	v_readlane_b32 s69, v254, 17
	s_and_saveexec_b64 s[36:37], vcc
	s_cbranch_execz .LBB0_465
	v_readlane_b32 s10, v253, 18
	v_lshlrev_b64 v[2:3], 12, v[0:1]
	v_readlane_b32 s11, v253, 19
	v_cmp_gt_i32_e32 vcc, s4, v94
	s_nop 0
	v_lshl_add_u64 v[10:11], s[10:11], 0, v[2:3]
	s_mov_b64 s[10:11], 0x800000
	v_lshl_add_u64 v[8:9], v[10:11], 0, s[10:11]
	s_mov_b64 s[10:11], 0x1000000
	v_lshl_add_u64 v[6:7], v[10:11], 0, s[10:11]
	s_mov_b64 s[10:11], 0x1800000
	v_lshl_add_u64 v[4:5], v[10:11], 0, s[10:11]
	v_lshl_add_u64 v[10:11], v[10:11], 0, v[84:85]
	v_lshl_add_u64 v[12:13], v[8:9], 0, v[84:85]
	global_load_dwordx4 v[22:25], v[10:11], off
	global_load_dwordx4 v[98:101], v[12:13], off
	v_lshl_add_u64 v[2:3], s[54:55], 0, v[2:3]
	s_waitcnt vmcnt(0)
	v_pk_add_f32 v[92:93], v[22:23], v[98:99]
	v_lshl_add_u64 v[22:23], v[6:7], 0, v[84:85]
	v_pk_add_f32 v[12:13], v[24:25], v[100:101]
	global_load_dwordx4 v[22:25], v[22:23], off
	s_waitcnt vmcnt(0)
	v_pk_add_f32 v[92:93], v[92:93], v[22:23]
	v_lshl_add_u64 v[22:23], v[4:5], 0, v[84:85]
	v_pk_add_f32 v[12:13], v[12:13], v[24:25]
	global_load_dwordx4 v[22:25], v[22:23], off
	s_waitcnt vmcnt(0)
	v_pk_add_f32 v[12:13], v[12:13], v[24:25]
	v_pk_add_f32 v[92:93], v[92:93], v[22:23]
	global_load_dwordx4 v[22:25], v[68:69], off
	s_waitcnt vmcnt(0)
	v_pk_fma_f32 v[56:57], v[12:13], v[24:25], v[56:57]
	v_pk_fma_f32 v[54:55], v[92:93], v[22:23], v[54:55]
	s_and_saveexec_b64 s[38:39], vcc
	s_cbranch_execz .LBB0_458
	v_mov_b32_e32 v85, v1
	v_lshl_add_u64 v[12:13], v[2:3], 0, v[84:85]
	global_store_dwordx4 v[12:13], v[54:57], off

.LBB0_465:
	s_or_b64 exec, exec, s[36:37]
	v_add_u32_e32 v92, s8, v66
	v_readlane_b32 s56, v254, 4
	v_min_i32_e32 v67, s6, v92
	v_readlane_b32 s71, v254, 19
	v_ashrrev_i32_e32 v2, 31, v67
	v_add_u32_e32 v0, 0xffff8000, v67
	v_cmp_gt_i32_e32 vcc, s40, v67
	v_mov_b32_e32 v4, s55
	v_readlane_b32 s70, v254, 18
	v_mov_b32_e32 v5, s71
	v_cndmask_b32_e32 v3, 0, v2, vcc
	v_cndmask_b32_e32 v2, v0, v67, vcc
	v_cndmask_b32_e32 v5, v4, v5, vcc
	v_mov_b32_e32 v4, s54
	v_mov_b32_e32 v6, s70
	v_cndmask_b32_e32 v4, v4, v6, vcc
	v_lshlrev_b64 v[2:3], 12, v[2:3]
	v_lshl_add_u64 v[2:3], v[4:5], 0, v[2:3]
	v_mov_b32_e32 v85, v1
	v_lshl_add_u64 v[2:3], v[2:3], 0, v[84:85]
	v_lshl_add_u64 v[212:213], v[2:3], 0, v[242:243]
	v_readfirstlane_b32 s98, v66
	s_sub_i32 s99, s98, 0x2000
	s_cmp_lt_u32 s99, 0x4800
	s_cbranch_scc0 .Lnp_1_3_ld
	v_mov_b64_e32 v[22:23], v[238:239]
	v_mov_b64_e32 v[24:25], v[240:241]
	v_mov_b64_e32 v[10:11], v[244:245]
	v_mov_b64_e32 v[12:13], v[246:247]
	ds_read_b128 v[6:9], v249
	ds_read_b128 v[2:5], v249 offset:1024
	s_branch .Lnp_1_3_pf
.Lnp_1_3_ld:
	global_load_dwordx4 v[22:25], v[2:3], off nt
	global_load_dwordx4 v[10:13], v[2:3], off offset:1024 nt
	global_load_dwordx4 v[6:9], v[2:3], off offset:2048 nt
	global_load_dwordx4 v[2:5], v[2:3], off offset:3072 nt
.Lnp_1_3_pf:
	s_cmp_lt_u32 s98, 0x4800
	s_cbranch_scc0 .Lnp_1_3_dn
	global_load_dwordx4 v[238:241], v[212:213], off nt
	global_load_dwordx4 v[244:247], v[212:213], off offset:1024 nt
	v_readfirstlane_b32 s99, v166
	s_lshr_b32 s99, s99, 6
	s_lshl_b32 s99, s99, 11
	s_add_i32 s99, s99, 0x13000
	v_add_u32_e32 v212, 0x800, v212
	s_mov_b32 m0, s99
	s_nop 0
	global_load_lds_dwordx4 v[212:213], off
	s_add_i32 s99, s99, 0x400
	v_add_u32_e32 v212, 0x400, v212
	s_mov_b32 m0, s99
	s_nop 0
	global_load_lds_dwordx4 v[212:213], off
.Lnp_1_3_dn:
	v_cmp_lt_i32_e32 vcc, s14, v67
	v_cmp_gt_i32_e64 s[10:11], s4, v92
	s_and_b64 vcc, vcc, s[10:11]
	v_readlane_b32 s57, v254, 5
	v_readlane_b32 s58, v254, 6
	v_readlane_b32 s59, v254, 7
	v_readlane_b32 s60, v254, 8
	v_readlane_b32 s61, v254, 9
	v_readlane_b32 s62, v254, 10
	v_readlane_b32 s63, v254, 11
	v_readlane_b32 s64, v254, 12
	v_readlane_b32 s65, v254, 13
	v_readlane_b32 s66, v254, 14
	v_readlane_b32 s67, v254, 15
	v_readlane_b32 s68, v254, 16
	v_readlane_b32 s69, v254, 17
	s_and_saveexec_b64 s[36:37], vcc
	s_cbranch_execz .LBB0_475
	v_readlane_b32 s10, v253, 18
	v_lshlrev_b64 v[98:99], 12, v[0:1]
	v_readlane_b32 s11, v253, 19
	v_cmp_gt_i32_e32 vcc, s4, v92
	s_nop 0
	v_lshl_add_u64 v[106:107], s[10:11], 0, v[98:99]
	s_mov_b64 s[10:11], 0x800000
	v_lshl_add_u64 v[104:105], v[106:107], 0, s[10:11]
	s_mov_b64 s[10:11], 0x1000000
	v_lshl_add_u64 v[102:103], v[106:107], 0, s[10:11]
	s_mov_b64 s[10:11], 0x1800000
	v_lshl_add_u64 v[100:101], v[106:107], 0, s[10:11]
	v_lshl_add_u64 v[106:107], v[106:107], 0, v[84:85]
	v_lshl_add_u64 v[118:119], v[104:105], 0, v[84:85]
	global_load_dwordx4 v[114:117], v[106:107], off
	v_lshl_add_u64 v[98:99], s[54:55], 0, v[98:99]
	global_load_dwordx4 v[118:121], v[118:119], off
	s_waitcnt vmcnt(0)
	v_pk_add_f32 v[118:119], v[114:115], v[118:119]
	v_lshl_add_u64 v[114:115], v[102:103], 0, v[84:85]
	v_pk_add_f32 v[120:121], v[116:117], v[120:121]
	global_load_dwordx4 v[114:117], v[114:115], off
	s_waitcnt vmcnt(0)
	v_pk_add_f32 v[118:119], v[118:119], v[114:115]
	v_lshl_add_u64 v[114:115], v[100:101], 0, v[84:85]
	v_pk_add_f32 v[120:121], v[120:121], v[116:117]
	global_load_dwordx4 v[114:117], v[114:115], off
	s_waitcnt vmcnt(0)
	v_pk_add_f32 v[120:121], v[120:121], v[116:117]
	v_pk_add_f32 v[118:119], v[118:119], v[114:115]
	global_load_dwordx4 v[114:117], v[68:69], off
	s_waitcnt vmcnt(0)
	v_pk_fma_f32 v[24:25], v[120:121], v[116:117], v[24:25]
	v_pk_fma_f32 v[22:23], v[118:119], v[114:115], v[22:23]
	s_and_saveexec_b64 s[38:39], vcc
	s_cbranch_execz .LBB0_468
	v_mov_b32_e32 v85, v1
	v_lshl_add_u64 v[114:115], v[98:99], 0, v[84:85]
	global_store_dwordx4 v[114:115], v[22:25], off

.LBB0_475:
	s_or_b64 exec, exec, s[36:37]
	v_readfirstlane_b32 s98, v66
	s_cmp_lt_u32 s98, 0x2000
	s_cbranch_scc0 .Lnp_1x_w1
	s_waitcnt vmcnt(4)
	s_branch .Lnp_1x_wd
.Lnp_1x_w1:
	s_cmp_lt_u32 s98, 0x6800
	s_cbranch_scc1 .Lnp_1x_wd
	s_waitcnt vmcnt(0)
.Lnp_1x_wd:
	s_waitcnt lgkmcnt(0)
	v_mul_f32_e32 v0, v63, v63
	v_mul_f32_e32 v67, v51, v51
	v_fmac_f32_e32 v0, v62, v62
	v_fmac_f32_e32 v67, v50, v50
	v_fmac_f32_e32 v0, v64, v64
	v_fmac_f32_e32 v67, v52, v52
	v_fmac_f32_e32 v0, v65, v65
	v_fmac_f32_e32 v67, v53, v53
	v_add_f32_e32 v0, v67, v0
	v_mul_f32_e32 v67, v47, v47
	v_fmac_f32_e32 v67, v46, v46
	v_fmac_f32_e32 v67, v48, v48
	v_fmac_f32_e32 v67, v49, v49
	v_add_f32_e32 v0, v67, v0
	v_mul_f32_e32 v67, v31, v31
	v_fmac_f32_e32 v67, v30, v30
	v_fmac_f32_e32 v67, v32, v32
	v_fmac_f32_e32 v67, v33, v33
	v_add_f32_e32 v0, v67, v0
	v_min_i32_e32 v67, 0x8000, v66
	v_ashrrev_i32_e32 v67, 12, v67
	v_lshl_add_u32 v222, v67, 13, v223
	v_mul_i32_i24_e32 v98, 0x1800, v67
	v_ashrrev_i32_e32 v99, 31, v98
	v_lshl_add_u64 v[100:101], v[98:99], 2, s[22:23]
	s_mov_b64 s[10:11], 0x1000
	v_lshl_add_u64 v[98:99], v[100:101], 0, s[10:11]
	v_mov_b32_e32 v85, v1
	v_lshl_add_u64 v[106:107], v[98:99], 0, v[84:85]
	ds_read_b128 v[102:105], v248
	ds_read_b128 v[114:117], v222 offset:4096
	v_lshl_add_u64 v[100:101], v[100:101], 0, v[84:85]
	ds_read_b128 v[118:121], v222
	v_mov_b32_e32 v87, v1
	v_mov_b32_e32 v89, v1
	v_mov_b32_e32 v91, v1
	ds_read_b128 v[168:171], v248 offset:1024
	v_lshl_add_u64 v[172:173], v[98:99], 0, v[86:87]
	ds_read_b128 v[172:175], v222 offset:5120
	ds_read_b128 v[176:179], v222 offset:1024
	ds_read_b128 v[180:183], v248 offset:2048
	v_lshl_add_u64 v[184:185], v[98:99], 0, v[88:89]
	ds_read_b128 v[184:187], v222 offset:6144
	ds_read_b128 v[188:191], v222 offset:2048
	ds_read_b128 v[192:195], v248 offset:3072
	v_lshl_add_u64 v[196:197], v[98:99], 0, v[90:91]
	ds_read_b128 v[196:199], v222 offset:7168
	ds_read_b128 v[200:203], v222 offset:3072
	ds_bpermute_b32 v67, v108, v0
	v_mov_b32_e32 v87, v1
	v_mov_b32_e32 v89, v1
	v_mov_b32_e32 v91, v1
	s_waitcnt lgkmcnt(0)
	v_add_f32_e32 v0, v0, v67
	ds_bpermute_b32 v67, v109, v0
	s_waitcnt lgkmcnt(0)
	v_add_f32_e32 v0, v0, v67
	ds_bpermute_b32 v67, v110, v0
	s_waitcnt lgkmcnt(0)
	v_add_f32_e32 v0, v0, v67
	ds_bpermute_b32 v67, v111, v0
	s_waitcnt lgkmcnt(0)
	v_add_f32_e32 v0, v0, v67
	ds_bpermute_b32 v67, v112, v0
	s_waitcnt lgkmcnt(0)
	v_add_f32_e32 v0, v0, v67
	ds_bpermute_b32 v67, v113, v0
	s_waitcnt lgkmcnt(0)
	v_add_f32_e32 v0, v0, v67
	v_fmamk_f32 v0, v0, 0x3a800000, v218
	v_cmp_gt_f32_e32 vcc, s13, v0
	v_mul_f32_e32 v67, 0x4b800000, v0
	s_nop 0
	v_cndmask_b32_e32 v0, v0, v67, vcc
	v_rsq_f32_e32 v0, v0
	s_nop 0
	v_mul_f32_e32 v67, 0x45800000, v0
	v_cndmask_b32_e32 v0, v0, v67, vcc
	v_pk_mul_f32 v[64:65], v[64:65], v[0:1] op_sel_hi:[1,0]
	v_pk_mul_f32 v[62:63], v[62:63], v[0:1] op_sel_hi:[1,0]
	v_pk_mul_f32 v[52:53], v[52:53], v[0:1] op_sel_hi:[1,0]
	v_pk_mul_f32 v[50:51], v[50:51], v[0:1] op_sel_hi:[1,0]
	v_pk_mul_f32 v[48:49], v[48:49], v[0:1] op_sel_hi:[1,0]
	v_pk_mul_f32 v[46:47], v[46:47], v[0:1] op_sel_hi:[1,0]
	v_pk_mul_f32 v[32:33], v[32:33], v[0:1] op_sel_hi:[1,0]
	v_pk_mul_f32 v[30:31], v[30:31], v[0:1] op_sel_hi:[1,0]
	v_cmp_gt_i32_e32 vcc, s4, v96
	s_waitcnt lgkmcnt(0)
	v_pk_mul_f32 v[62:63], v[102:103], v[62:63]
	v_pk_mul_f32 v[64:65], v[104:105], v[64:65]
	s_waitcnt lgkmcnt(0)
	v_pk_add_f32 v[102:103], v[116:117], 1.0 op_sel_hi:[1,0]
	v_pk_add_f32 v[104:105], v[114:115], 1.0 op_sel_hi:[1,0]
	s_waitcnt lgkmcnt(0)
	v_pk_fma_f32 v[64:65], v[102:103], v[64:65], v[120:121]
	v_pk_fma_f32 v[62:63], v[104:105], v[62:63], v[118:119]
	v_lshl_add_u64 v[102:103], v[98:99], 0, v[86:87]
	v_cvt_pk_bf16_f32 v62, v62, v63
	v_cvt_pk_bf16_f32 v63, v64, v65
	global_store_dwordx2 v[82:83], v[62:63], off
	s_waitcnt lgkmcnt(0)
	v_pk_mul_f32 v[50:51], v[168:169], v[50:51]
	v_pk_mul_f32 v[52:53], v[170:171], v[52:53]
	v_pk_add_f32 v[62:63], v[174:175], 1.0 op_sel_hi:[1, 0]
	v_pk_add_f32 v[64:65], v[172:173], 1.0 op_sel_hi:[1, 0]
	v_pk_fma_f32 v[52:53], v[62:63], v[52:53], v[178:179]
	v_pk_fma_f32 v[50:51], v[64:65], v[50:51], v[176:177]
	v_lshl_add_u64 v[62:63], v[98:99], 0, v[88:89]
	v_cvt_pk_bf16_f32 v50, v50, v51
	v_cvt_pk_bf16_f32 v51, v52, v53
	global_store_dwordx2 v[82:83], v[50:51], off offset:512
	s_waitcnt lgkmcnt(0)
	v_pk_mul_f32 v[46:47], v[180:181], v[46:47]
	v_pk_mul_f32 v[48:49], v[182:183], v[48:49]
	v_pk_add_f32 v[50:51], v[186:187], 1.0 op_sel_hi:[1, 0]
	v_pk_add_f32 v[52:53], v[184:185], 1.0 op_sel_hi:[1, 0]
	v_pk_fma_f32 v[48:49], v[50:51], v[48:49], v[190:191]
	v_pk_fma_f32 v[46:47], v[52:53], v[46:47], v[188:189]
	v_lshl_add_u64 v[50:51], v[98:99], 0, v[90:91]
	v_cvt_pk_bf16_f32 v46, v46, v47
	v_cvt_pk_bf16_f32 v47, v48, v49
	global_store_dwordx2 v[82:83], v[46:47], off offset:1024
	s_waitcnt lgkmcnt(0)
	v_pk_mul_f32 v[30:31], v[30:31], v[192:193]
	v_pk_mul_f32 v[32:33], v[32:33], v[194:195]
	v_pk_add_f32 v[46:47], v[198:199], 1.0 op_sel_hi:[1, 0]
	v_pk_add_f32 v[48:49], v[196:197], 1.0 op_sel_hi:[1, 0]
	v_pk_fma_f32 v[32:33], v[32:33], v[46:47], v[202:203]
	v_pk_fma_f32 v[30:31], v[30:31], v[48:49], v[200:201]
	s_nop 0
	v_cvt_pk_bf16_f32 v30, v30, v31
	v_cvt_pk_bf16_f32 v31, v32, v33
	global_store_dwordx2 v[82:83], v[30:31], off offset:1536
	s_and_saveexec_b64 s[36:37], vcc
	s_cbranch_execz .LBB0_478
	v_mul_f32_e32 v0, v59, v59
	v_mul_f32_e32 v30, v43, v43
	v_fmac_f32_e32 v0, v58, v58
	v_fmac_f32_e32 v30, v42, v42
	v_fmac_f32_e32 v0, v60, v60
	v_fmac_f32_e32 v30, v44, v44
	v_fmac_f32_e32 v0, v61, v61
	v_fmac_f32_e32 v30, v45, v45
	v_add_f32_e32 v0, v30, v0
	v_mul_f32_e32 v30, v39, v39
	v_fmac_f32_e32 v30, v38, v38
	v_fmac_f32_e32 v30, v40, v40
	v_fmac_f32_e32 v30, v41, v41
	v_add_f32_e32 v0, v30, v0
	v_mul_f32_e32 v30, v35, v35
	v_fmac_f32_e32 v30, v34, v34
	v_fmac_f32_e32 v30, v36, v36
	v_fmac_f32_e32 v30, v37, v37
	v_add_f32_e32 v0, v30, v0
	ds_bpermute_b32 v46, v108, v0
	v_min_i32_e32 v30, 0x8000, v96
	v_ashrrev_i32_e32 v30, 12, v30
	v_lshl_add_u32 v222, v30, 13, v223
	v_mul_i32_i24_e32 v30, 0x1800, v30
	v_ashrrev_i32_e32 v31, 31, v30
	s_waitcnt lgkmcnt(0)
	v_add_f32_e32 v0, v0, v46
	ds_bpermute_b32 v46, v109, v0
	v_lshl_add_u64 v[32:33], v[30:31], 2, s[22:23]
	v_lshl_add_u64 v[30:31], v[32:33], 0, s[10:11]
	v_lshl_add_u64 v[52:53], v[30:31], 0, v[84:85]
	v_ashrrev_i32_e32 v97, 31, v96
	s_waitcnt lgkmcnt(0)
	v_add_f32_e32 v0, v0, v46
	ds_bpermute_b32 v46, v110, v0
	ds_read_b128 v[48:51], v248
	ds_read_b128 v[62:65], v222 offset:4096
	v_lshl_add_u64 v[32:33], v[32:33], 0, v[84:85]
	s_waitcnt lgkmcnt(0)
	v_add_f32_e32 v0, v0, v46
	ds_bpermute_b32 v46, v111, v0
	s_waitcnt lgkmcnt(0)
	v_add_f32_e32 v0, v0, v46
	ds_bpermute_b32 v46, v112, v0
	s_waitcnt lgkmcnt(0)
	v_add_f32_e32 v0, v0, v46
	ds_bpermute_b32 v46, v113, v0
	s_waitcnt lgkmcnt(0)
	v_add_f32_e32 v0, v0, v46
	v_fmamk_f32 v0, v0, 0x3a800000, v218
	v_cmp_gt_f32_e32 vcc, s13, v0
	v_mul_f32_e32 v46, 0x4b800000, v0
	s_nop 0
	v_cndmask_b32_e32 v0, v0, v46, vcc
	v_rsq_f32_e32 v0, v0
	s_nop 0
	v_mul_f32_e32 v46, 0x45800000, v0
	v_cndmask_b32_e32 v0, v0, v46, vcc
	v_lshlrev_b64 v[46:47], 11, v[96:97]
	ds_read_b128 v[96:99], v222
	v_mov_b32_e32 v87, v1
	v_mov_b32_e32 v89, v1
	v_mov_b32_e32 v91, v1
	ds_read_b128 v[168:171], v248 offset:1024
	v_lshl_add_u64 v[172:173], v[30:31], 0, v[86:87]
	ds_read_b128 v[172:175], v222 offset:5120
	ds_read_b128 v[176:179], v222 offset:1024
	ds_read_b128 v[180:183], v248 offset:2048
	v_lshl_add_u64 v[184:185], v[30:31], 0, v[88:89]
	ds_read_b128 v[184:187], v222 offset:6144
	ds_read_b128 v[188:191], v222 offset:2048
	ds_read_b128 v[192:195], v248 offset:3072
	v_lshl_add_u64 v[196:197], v[30:31], 0, v[90:91]
	ds_read_b128 v[196:199], v222 offset:7168
	ds_read_b128 v[200:203], v222 offset:3072
	v_pk_mul_f32 v[52:53], v[60:61], v[0:1] op_sel_hi:[1,0]
	v_pk_mul_f32 v[58:59], v[58:59], v[0:1] op_sel_hi:[1,0]
	v_pk_mul_f32 v[44:45], v[44:45], v[0:1] op_sel_hi:[1,0]
	v_pk_mul_f32 v[42:43], v[42:43], v[0:1] op_sel_hi:[1,0]
	v_pk_mul_f32 v[40:41], v[40:41], v[0:1] op_sel_hi:[1,0]
	v_pk_mul_f32 v[38:39], v[38:39], v[0:1] op_sel_hi:[1,0]
	v_pk_mul_f32 v[36:37], v[36:37], v[0:1] op_sel_hi:[1,0]
	v_pk_mul_f32 v[34:35], v[34:35], v[0:1] op_sel_hi:[1,0]
	s_waitcnt lgkmcnt(0)
	v_pk_mul_f32 v[48:49], v[48:49], v[58:59]
	v_pk_mul_f32 v[50:51], v[50:51], v[52:53]
	s_waitcnt lgkmcnt(0)
	v_pk_add_f32 v[52:53], v[64:65], 1.0 op_sel_hi:[1,0]
	v_pk_add_f32 v[58:59], v[62:63], 1.0 op_sel_hi:[1,0]
	v_lshl_add_u64 v[62:63], v[80:81], 0, v[46:47]
	s_waitcnt lgkmcnt(0)
	v_pk_fma_f32 v[50:51], v[52:53], v[50:51], v[98:99]
	v_pk_fma_f32 v[48:49], v[58:59], v[48:49], v[96:97]
	s_nop 0
	v_cvt_pk_bf16_f32 v48, v48, v49
	v_cvt_pk_bf16_f32 v49, v50, v51
	global_store_dwordx2 v[62:63], v[48:49], off
	v_lshl_add_u64 v[50:51], v[30:31], 0, v[86:87]
	s_waitcnt lgkmcnt(0)
	v_pk_mul_f32 v[42:43], v[168:169], v[42:43]
	v_pk_mul_f32 v[44:45], v[170:171], v[44:45]
	v_pk_add_f32 v[46:47], v[174:175], 1.0 op_sel_hi:[1, 0]
	v_pk_add_f32 v[48:49], v[172:173], 1.0 op_sel_hi:[1, 0]
	v_pk_fma_f32 v[44:45], v[46:47], v[44:45], v[178:179]
	v_pk_fma_f32 v[42:43], v[48:49], v[42:43], v[176:177]
	v_lshl_add_u64 v[46:47], v[30:31], 0, v[88:89]
	v_cvt_pk_bf16_f32 v42, v42, v43
	v_cvt_pk_bf16_f32 v43, v44, v45
	global_store_dwordx2 v[62:63], v[42:43], off offset:512
	v_lshl_add_u64 v[30:31], v[30:31], 0, v[90:91]
	s_waitcnt lgkmcnt(0)
	v_pk_mul_f32 v[38:39], v[180:181], v[38:39]
	v_pk_mul_f32 v[40:41], v[182:183], v[40:41]
	v_pk_add_f32 v[42:43], v[186:187], 1.0 op_sel_hi:[1, 0]
	v_pk_add_f32 v[44:45], v[184:185], 1.0 op_sel_hi:[1, 0]
	v_pk_fma_f32 v[40:41], v[42:43], v[40:41], v[190:191]
	v_pk_fma_f32 v[38:39], v[44:45], v[38:39], v[188:189]
	s_nop 0
	v_cvt_pk_bf16_f32 v38, v38, v39
	v_cvt_pk_bf16_f32 v39, v40, v41
	global_store_dwordx2 v[62:63], v[38:39], off offset:1024
	s_waitcnt lgkmcnt(0)
	v_pk_mul_f32 v[34:35], v[34:35], v[192:193]
	v_pk_mul_f32 v[36:37], v[36:37], v[194:195]
	v_pk_add_f32 v[38:39], v[198:199], 1.0 op_sel_hi:[1, 0]
	v_pk_add_f32 v[40:41], v[196:197], 1.0 op_sel_hi:[1, 0]
	v_pk_fma_f32 v[32:33], v[36:37], v[38:39], v[202:203]
	v_pk_fma_f32 v[30:31], v[34:35], v[40:41], v[200:201]
	s_nop 0
	v_cvt_pk_bf16_f32 v30, v30, v31
	v_cvt_pk_bf16_f32 v31, v32, v33
	global_store_dwordx2 v[62:63], v[30:31], off offset:1536
	s_or_b64 exec, exec, s[36:37]
	v_cmp_gt_i32_e32 vcc, s4, v94
	s_and_saveexec_b64 s[36:37], vcc
	s_cbranch_execnz .LBB0_479

.LBB0_479:
	v_mul_f32_e32 v0, v55, v55
	v_mul_f32_e32 v30, v27, v27
	v_fmac_f32_e32 v0, v54, v54
	v_fmac_f32_e32 v30, v26, v26
	v_fmac_f32_e32 v0, v56, v56
	v_fmac_f32_e32 v30, v28, v28
	v_fmac_f32_e32 v0, v57, v57
	v_fmac_f32_e32 v30, v29, v29
	v_add_f32_e32 v0, v30, v0
	v_mul_f32_e32 v30, v19, v19
	v_fmac_f32_e32 v30, v18, v18
	v_fmac_f32_e32 v30, v20, v20
	v_fmac_f32_e32 v30, v21, v21
	v_add_f32_e32 v0, v30, v0
	v_mul_f32_e32 v30, v15, v15
	v_fmac_f32_e32 v30, v14, v14
	v_fmac_f32_e32 v30, v16, v16
	v_fmac_f32_e32 v30, v17, v17
	v_add_f32_e32 v0, v30, v0
	v_min_i32_e32 v30, 0x8000, v94
	v_ashrrev_i32_e32 v30, 12, v30
	v_lshl_add_u32 v222, v30, 13, v223
	v_mul_i32_i24_e32 v30, 0x1800, v30
	v_ashrrev_i32_e32 v31, 31, v30
	v_lshl_add_u64 v[36:37], v[30:31], 2, s[22:23]
	ds_bpermute_b32 v30, v108, v0
	v_lshl_add_u64 v[34:35], v[36:37], 0, s[10:11]
	v_mov_b32_e32 v85, v1
	v_lshl_add_u64 v[38:39], v[34:35], 0, v[84:85]
	ds_read_b128 v[40:43], v222 offset:4096
	s_waitcnt lgkmcnt(0)
	v_add_f32_e32 v0, v0, v30
	ds_bpermute_b32 v30, v109, v0
	v_lshl_add_u64 v[38:39], v[36:37], 0, v[84:85]
	ds_read_b128 v[44:47], v222
	v_ashrrev_i32_e32 v95, 31, v94
	v_lshlrev_b64 v[48:49], 11, v[94:95]
	s_waitcnt lgkmcnt(0)
	v_add_f32_e32 v0, v0, v30
	ds_bpermute_b32 v30, v110, v0
	v_mov_b32_e32 v87, v1
	v_mov_b32_e32 v89, v1
	v_mov_b32_e32 v91, v1
	s_waitcnt lgkmcnt(0)
	v_add_f32_e32 v0, v0, v30
	ds_bpermute_b32 v30, v111, v0
	s_waitcnt lgkmcnt(0)
	v_add_f32_e32 v0, v0, v30
	ds_bpermute_b32 v30, v112, v0
	s_waitcnt lgkmcnt(0)
	v_add_f32_e32 v0, v0, v30
	ds_bpermute_b32 v30, v113, v0
	s_waitcnt lgkmcnt(0)
	v_add_f32_e32 v0, v0, v30
	v_fmamk_f32 v0, v0, 0x3a800000, v218
	v_cmp_gt_f32_e32 vcc, s13, v0
	v_mul_f32_e32 v30, 0x4b800000, v0
	s_waitcnt lgkmcnt(0)
	v_pk_add_f32 v[40:41], v[40:41], 1.0 op_sel_hi:[1,0]
	v_cndmask_b32_e32 v0, v0, v30, vcc
	v_rsq_f32_e32 v0, v0
	s_nop 0
	v_mul_f32_e32 v30, 0x45800000, v0
	v_cndmask_b32_e32 v0, v0, v30, vcc
	ds_read_b128 v[30:33], v248
	v_mov_b32_e32 v87, v1
	v_mov_b32_e32 v89, v1
	v_mov_b32_e32 v91, v1
	ds_read_b128 v[168:171], v248 offset:1024
	v_lshl_add_u64 v[172:173], v[34:35], 0, v[86:87]
	ds_read_b128 v[172:175], v222 offset:5120
	ds_read_b128 v[176:179], v222 offset:1024
	ds_read_b128 v[180:183], v248 offset:2048
	v_lshl_add_u64 v[184:185], v[34:35], 0, v[88:89]
	ds_read_b128 v[184:187], v222 offset:6144
	ds_read_b128 v[188:191], v222 offset:2048
	ds_read_b128 v[192:195], v248 offset:3072
	v_lshl_add_u64 v[196:197], v[34:35], 0, v[90:91]
	ds_read_b128 v[196:199], v222 offset:7168
	ds_read_b128 v[200:203], v222 offset:3072
	v_pk_mul_f32 v[36:37], v[56:57], v[0:1] op_sel_hi:[1,0]
	v_pk_mul_f32 v[50:51], v[54:55], v[0:1] op_sel_hi:[1,0]
	v_pk_mul_f32 v[28:29], v[28:29], v[0:1] op_sel_hi:[1,0]
	v_pk_mul_f32 v[26:27], v[26:27], v[0:1] op_sel_hi:[1,0]
	v_pk_mul_f32 v[20:21], v[20:21], v[0:1] op_sel_hi:[1,0]
	v_pk_mul_f32 v[18:19], v[18:19], v[0:1] op_sel_hi:[1,0]
	v_pk_mul_f32 v[16:17], v[16:17], v[0:1] op_sel_hi:[1,0]
	v_pk_mul_f32 v[14:15], v[14:15], v[0:1] op_sel_hi:[1,0]
	s_waitcnt lgkmcnt(0)
	v_pk_mul_f32 v[30:31], v[30:31], v[50:51]
	v_pk_mul_f32 v[32:33], v[32:33], v[36:37]
	v_pk_add_f32 v[36:37], v[42:43], 1.0 op_sel_hi:[1,0]
	v_pk_fma_f32 v[30:31], v[40:41], v[30:31], v[44:45]
	v_pk_fma_f32 v[32:33], v[36:37], v[32:33], v[46:47]
	v_cvt_pk_bf16_f32 v30, v30, v31
	v_cvt_pk_bf16_f32 v31, v32, v33
	v_lshl_add_u64 v[36:37], v[80:81], 0, v[48:49]
	global_store_dwordx2 v[36:37], v[30:31], off
	v_lshl_add_u64 v[40:41], v[34:35], 0, v[86:87]
	s_waitcnt lgkmcnt(0)
	v_pk_mul_f32 v[26:27], v[168:169], v[26:27]
	v_pk_mul_f32 v[28:29], v[170:171], v[28:29]
	v_pk_add_f32 v[30:31], v[174:175], 1.0 op_sel_hi:[1, 0]
	v_pk_add_f32 v[32:33], v[172:173], 1.0 op_sel_hi:[1, 0]
	v_pk_fma_f32 v[28:29], v[30:31], v[28:29], v[178:179]
	v_pk_fma_f32 v[26:27], v[32:33], v[26:27], v[176:177]
	v_lshl_add_u64 v[30:31], v[34:35], 0, v[88:89]
	v_cvt_pk_bf16_f32 v26, v26, v27
	v_cvt_pk_bf16_f32 v27, v28, v29
	global_store_dwordx2 v[36:37], v[26:27], off offset:512
	s_waitcnt lgkmcnt(0)
	v_pk_mul_f32 v[18:19], v[180:181], v[18:19]
	v_pk_mul_f32 v[20:21], v[182:183], v[20:21]
	v_pk_add_f32 v[26:27], v[186:187], 1.0 op_sel_hi:[1, 0]
	v_pk_add_f32 v[28:29], v[184:185], 1.0 op_sel_hi:[1, 0]
	v_pk_fma_f32 v[20:21], v[26:27], v[20:21], v[190:191]
	v_pk_fma_f32 v[18:19], v[28:29], v[18:19], v[188:189]
	v_lshl_add_u64 v[26:27], v[34:35], 0, v[90:91]
	v_cvt_pk_bf16_f32 v18, v18, v19
	v_cvt_pk_bf16_f32 v19, v20, v21
	global_store_dwordx2 v[36:37], v[18:19], off offset:1024
	s_waitcnt lgkmcnt(0)
	v_pk_mul_f32 v[14:15], v[14:15], v[192:193]
	v_pk_mul_f32 v[16:17], v[16:17], v[194:195]
	v_pk_add_f32 v[18:19], v[198:199], 1.0 op_sel_hi:[1, 0]
	v_pk_add_f32 v[20:21], v[196:197], 1.0 op_sel_hi:[1, 0]
	v_pk_fma_f32 v[16:17], v[16:17], v[18:19], v[202:203]
	v_pk_fma_f32 v[14:15], v[14:15], v[20:21], v[200:201]
	s_nop 0
	v_cvt_pk_bf16_f32 v14, v14, v15
	v_cvt_pk_bf16_f32 v15, v16, v17
	global_store_dwordx2 v[36:37], v[14:15], off offset:1536
	s_or_b64 exec, exec, s[36:37]
	v_cmp_gt_i32_e32 vcc, s4, v92
	s_and_saveexec_b64 s[36:37], vcc
	s_cbranch_execz .LBB0_442
.LBB0_480:
	v_mul_f32_e32 v0, v23, v23
	v_mul_f32_e32 v14, v11, v11
	v_fmac_f32_e32 v0, v22, v22
	v_fmac_f32_e32 v14, v10, v10
	v_fmac_f32_e32 v0, v24, v24
	v_fmac_f32_e32 v14, v12, v12
	v_fmac_f32_e32 v0, v25, v25
	v_fmac_f32_e32 v14, v13, v13
	v_add_f32_e32 v0, v14, v0
	v_mul_f32_e32 v14, v7, v7
	v_fmac_f32_e32 v14, v6, v6
	v_fmac_f32_e32 v14, v8, v8
	v_fmac_f32_e32 v14, v9, v9
	v_add_f32_e32 v0, v14, v0
	v_mul_f32_e32 v14, v3, v3
	v_fmac_f32_e32 v14, v2, v2
	v_fmac_f32_e32 v14, v4, v4
	v_fmac_f32_e32 v14, v5, v5
	v_add_f32_e32 v0, v14, v0
	v_min_i32_e32 v14, 0x8000, v92
	v_ashrrev_i32_e32 v14, 12, v14
	v_lshl_add_u32 v222, v14, 13, v223
	v_mul_i32_i24_e32 v14, 0x1800, v14
	v_ashrrev_i32_e32 v15, 31, v14
	v_lshl_add_u64 v[20:21], v[14:15], 2, s[22:23]
	ds_bpermute_b32 v14, v108, v0
	v_lshl_add_u64 v[18:19], v[20:21], 0, s[10:11]
	v_mov_b32_e32 v85, v1
	v_lshl_add_u64 v[26:27], v[18:19], 0, v[84:85]
	ds_read_b128 v[28:31], v222 offset:4096
	s_waitcnt lgkmcnt(0)
	v_add_f32_e32 v0, v0, v14
	ds_bpermute_b32 v14, v109, v0
	v_lshl_add_u64 v[26:27], v[20:21], 0, v[84:85]
	ds_read_b128 v[32:35], v222
	v_ashrrev_i32_e32 v93, 31, v92
	v_lshlrev_b64 v[36:37], 11, v[92:93]
	s_waitcnt lgkmcnt(0)
	v_add_f32_e32 v0, v0, v14
	ds_bpermute_b32 v14, v110, v0
	v_mov_b32_e32 v87, v1
	v_mov_b32_e32 v89, v1
	v_mov_b32_e32 v91, v1
	s_waitcnt lgkmcnt(0)
	v_add_f32_e32 v0, v0, v14
	ds_bpermute_b32 v14, v111, v0
	s_waitcnt lgkmcnt(0)
	v_add_f32_e32 v0, v0, v14
	ds_bpermute_b32 v14, v112, v0
	s_waitcnt lgkmcnt(0)
	v_add_f32_e32 v0, v0, v14
	ds_bpermute_b32 v14, v113, v0
	s_waitcnt lgkmcnt(0)
	v_add_f32_e32 v0, v0, v14
	v_fmamk_f32 v0, v0, 0x3a800000, v218
	v_cmp_gt_f32_e32 vcc, s13, v0
	v_mul_f32_e32 v14, 0x4b800000, v0
	s_nop 0
	v_cndmask_b32_e32 v0, v0, v14, vcc
	v_rsq_f32_e32 v0, v0
	s_nop 0
	v_mul_f32_e32 v14, 0x45800000, v0
	v_cndmask_b32_e32 v0, v0, v14, vcc
	ds_read_b128 v[14:17], v248
	v_mov_b32_e32 v87, v1
	v_mov_b32_e32 v89, v1
	v_mov_b32_e32 v91, v1
	ds_read_b128 v[168:171], v248 offset:1024
	v_lshl_add_u64 v[172:173], v[18:19], 0, v[86:87]
	ds_read_b128 v[172:175], v222 offset:5120
	ds_read_b128 v[176:179], v222 offset:1024
	ds_read_b128 v[180:183], v248 offset:2048
	v_lshl_add_u64 v[184:185], v[18:19], 0, v[88:89]
	ds_read_b128 v[184:187], v222 offset:6144
	ds_read_b128 v[188:191], v222 offset:2048
	ds_read_b128 v[192:195], v248 offset:3072
	v_lshl_add_u64 v[196:197], v[18:19], 0, v[90:91]
	ds_read_b128 v[196:199], v222 offset:7168
	ds_read_b128 v[200:203], v222 offset:3072
	v_pk_mul_f32 v[20:21], v[24:25], v[0:1] op_sel_hi:[1,0]
	v_pk_mul_f32 v[22:23], v[22:23], v[0:1] op_sel_hi:[1,0]
	v_pk_mul_f32 v[12:13], v[12:13], v[0:1] op_sel_hi:[1,0]
	v_pk_mul_f32 v[10:11], v[10:11], v[0:1] op_sel_hi:[1,0]
	v_pk_mul_f32 v[8:9], v[8:9], v[0:1] op_sel_hi:[1,0]
	v_pk_mul_f32 v[6:7], v[6:7], v[0:1] op_sel_hi:[1,0]
	v_pk_mul_f32 v[4:5], v[4:5], v[0:1] op_sel_hi:[1,0]
	v_pk_mul_f32 v[2:3], v[2:3], v[0:1] op_sel_hi:[1,0]
	s_waitcnt lgkmcnt(0)
	v_pk_mul_f32 v[14:15], v[14:15], v[22:23]
	v_pk_mul_f32 v[16:17], v[16:17], v[20:21]
	v_pk_add_f32 v[20:21], v[30:31], 1.0 op_sel_hi:[1,0]
	v_pk_add_f32 v[22:23], v[28:29], 1.0 op_sel_hi:[1,0]
	v_pk_fma_f32 v[16:17], v[20:21], v[16:17], v[34:35]
	v_pk_fma_f32 v[14:15], v[22:23], v[14:15], v[32:33]
	v_lshl_add_u64 v[20:21], v[80:81], 0, v[36:37]
	v_cvt_pk_bf16_f32 v14, v14, v15
	v_cvt_pk_bf16_f32 v15, v16, v17
	global_store_dwordx2 v[20:21], v[14:15], off
	v_lshl_add_u64 v[22:23], v[18:19], 0, v[86:87]
	s_waitcnt lgkmcnt(0)
	v_pk_mul_f32 v[10:11], v[168:169], v[10:11]
	v_pk_mul_f32 v[12:13], v[170:171], v[12:13]
	v_pk_add_f32 v[14:15], v[174:175], 1.0 op_sel_hi:[1, 0]
	v_pk_add_f32 v[16:17], v[172:173], 1.0 op_sel_hi:[1, 0]
	v_pk_fma_f32 v[12:13], v[14:15], v[12:13], v[178:179]
	v_pk_fma_f32 v[10:11], v[16:17], v[10:11], v[176:177]
	v_lshl_add_u64 v[14:15], v[18:19], 0, v[88:89]
	v_cvt_pk_bf16_f32 v10, v10, v11
	v_cvt_pk_bf16_f32 v11, v12, v13
	global_store_dwordx2 v[20:21], v[10:11], off offset:512
	s_waitcnt lgkmcnt(0)
	v_pk_mul_f32 v[6:7], v[180:181], v[6:7]
	v_pk_mul_f32 v[8:9], v[182:183], v[8:9]
	v_pk_add_f32 v[10:11], v[186:187], 1.0 op_sel_hi:[1, 0]
	v_pk_add_f32 v[12:13], v[184:185], 1.0 op_sel_hi:[1, 0]
	v_pk_fma_f32 v[8:9], v[10:11], v[8:9], v[190:191]
	v_pk_fma_f32 v[6:7], v[12:13], v[6:7], v[188:189]
	v_lshl_add_u64 v[10:11], v[18:19], 0, v[90:91]
	v_cvt_pk_bf16_f32 v6, v6, v7
	v_cvt_pk_bf16_f32 v7, v8, v9
	global_store_dwordx2 v[20:21], v[6:7], off offset:1024
	s_waitcnt lgkmcnt(0)
	v_pk_mul_f32 v[2:3], v[2:3], v[192:193]
	v_pk_mul_f32 v[4:5], v[4:5], v[194:195]
	v_pk_add_f32 v[6:7], v[198:199], 1.0 op_sel_hi:[1, 0]
	v_pk_add_f32 v[8:9], v[196:197], 1.0 op_sel_hi:[1, 0]
	v_pk_fma_f32 v[4:5], v[4:5], v[6:7], v[202:203]
	v_pk_fma_f32 v[2:3], v[2:3], v[8:9], v[200:201]
	s_nop 0
	v_cvt_pk_bf16_f32 v2, v2, v3
	v_cvt_pk_bf16_f32 v3, v4, v5
	global_store_dwordx2 v[20:21], v[2:3], off offset:1536
	s_branch .LBB0_442
	s_nop 0
	s_nop 0
	s_nop 0
	s_nop 0
	s_nop 0
	s_nop 0
	s_nop 0
	s_nop 0
	s_nop 0
	s_nop 0
	s_nop 0
	s_nop 0
	s_nop 0
	s_nop 0
	s_nop 0
	s_nop 0
	s_nop 0
	s_nop 0
	s_nop 0
	s_nop 0
	s_nop 0
	s_nop 0
	s_nop 0
	s_nop 0
	s_nop 0
	s_nop 0
	s_nop 0
	s_nop 0
	s_nop 0
	s_nop 0
	s_nop 0
	s_nop 0
	s_nop 0
	s_nop 0
	s_nop 0
	s_nop 0
	s_nop 0
	s_nop 0
	s_nop 0
	s_nop 0
	s_nop 0
	s_nop 0
	s_nop 0
	s_nop 0
	s_nop 0
	s_nop 0
	s_nop 0
	s_nop 0
	s_nop 0
	s_nop 0
	s_nop 0
	s_nop 0
	s_nop 0
	s_nop 0
	s_nop 0
	s_nop 0
	s_nop 0
	s_nop 0
	s_nop 0
	s_nop 0
	s_nop 0
	s_nop 0
	s_nop 0
	s_nop 0
	s_nop 0
	s_nop 0
	s_nop 0
	s_nop 0
	s_nop 0
	s_nop 0
	s_nop 0
	s_nop 0
	s_nop 0
	s_nop 0
	s_nop 0
	s_nop 0
	s_nop 0
	s_nop 0
	s_nop 0
	s_nop 0
	s_nop 0
	s_nop 0
	s_nop 0
	s_nop 0
	s_nop 0
	s_nop 0
	s_nop 0
	s_nop 0
	s_nop 0
	s_nop 0
	s_nop 0
	s_nop 0
	s_nop 0
	s_nop 0
	s_nop 0
	s_nop 0
	s_nop 0
	s_nop 0
	s_nop 0
	s_nop 0
	s_nop 0
	s_nop 0
	s_nop 0
	s_nop 0
	s_nop 0
	s_nop 0
	s_nop 0
	s_nop 0
	s_nop 0
	s_nop 0
	s_nop 0
	s_nop 0
	s_nop 0
	s_nop 0
	s_nop 0
	s_nop 0
	s_nop 0
	s_nop 0
	s_nop 0
	s_nop 0
	s_nop 0
	s_nop 0
	s_nop 0

.LBB0_527:
	v_ashrrev_i32_e32 v0, 6, v166
	v_readlane_b32 s0, v252, 17
	s_nop 1
	v_add_u32_e32 v66, s0, v0
	v_cmp_gt_i32_e32 vcc, s15, v66
	s_and_saveexec_b64 s[0:1], vcc
	s_cbranch_execz .LBB0_568
	v_and_b32_e32 v3, 64, v220
	v_add_u32_e32 v3, 64, v3
	v_xor_b32_e32 v5, 32, v220
	v_cmp_lt_i32_e32 vcc, v5, v3
	s_waitcnt lgkmcnt(0)
	s_load_dword s8, s[96:97], 0x0
	v_readlane_b32 s2, v254, 57
	v_cndmask_b32_e32 v5, v220, v5, vcc
	v_lshlrev_b32_e32 v102, 2, v5
	v_xor_b32_e32 v5, 16, v220
	v_cmp_lt_i32_e32 vcc, v5, v3
	v_readlane_b32 s3, v254, 58
	s_lshl_b32 s2, s2, 10
	v_cndmask_b32_e32 v5, v220, v5, vcc
	v_lshlrev_b32_e32 v103, 2, v5
	v_xor_b32_e32 v5, 8, v220
	v_cmp_lt_i32_e32 vcc, v5, v3
	s_ashr_i32 s3, s2, 31
	v_lshlrev_b32_e32 v0, 2, v166
	v_cndmask_b32_e32 v5, v220, v5, vcc
	v_lshlrev_b32_e32 v104, 2, v5
	v_xor_b32_e32 v5, 4, v220
	v_cmp_lt_i32_e32 vcc, v5, v3
	s_lshl_b64 s[2:3], s[2:3], 2
	s_waitcnt lgkmcnt(0)
	s_lshl_b32 s4, s8, 3
	v_cndmask_b32_e32 v5, v220, v5, vcc
	s_add_u32 s6, s84, s2
	v_and_b32_e32 v2, 0xfc, v0
	v_lshlrev_b32_e32 v105, 2, v5
	v_xor_b32_e32 v5, 2, v220
	s_addc_u32 s7, s85, s3
	v_lshlrev_b32_e32 v0, 2, v2
	v_cmp_lt_i32_e32 vcc, v5, v3
	v_lshl_add_u64 v[70:71], s[6:7], 0, v[0:1]
	v_readlane_b32 s6, v253, 39
	v_cndmask_b32_e32 v5, v220, v5, vcc
	s_cmp_lg_u64 s[30:31], 0
	v_lshl_add_u64 v[68:69], s[30:31], 0, v[0:1]
	v_lshlrev_b32_e32 v106, 2, v5
	v_xor_b32_e32 v5, 1, v220
	v_lshl_add_u64 v[72:73], s[54:55], 0, v[0:1]
	v_lshlrev_b32_e32 v0, 1, v2
	v_readlane_b32 s7, v253, 40
	v_ashrrev_i32_e32 v67, 31, v66
	s_cselect_b64 s[22:23], -1, 0
	s_lshl_b32 s24, s8, 5
	v_cmp_lt_i32_e32 vcc, v5, v3
	v_lshl_add_u64 v[74:75], s[6:7], 0, v[0:1]
	v_lshlrev_b64 v[10:11], 11, v[66:67]
	v_and_b32_e32 v0, 63, v166
	v_or_b32_e32 v4, 0x100, v2
	v_or_b32_e32 v6, 0x200, v2
	v_or_b32_e32 v8, 0x300, v2
	v_cndmask_b32_e32 v3, v220, v5, vcc
	v_lshl_or_b32 v10, v0, 3, v10
	s_ashr_i32 s25, s24, 31
	s_mov_b64 s[2:3], 0
	v_lshlrev_b32_e32 v107, 2, v3
	v_lshl_add_u64 v[76:77], s[6:7], 0, v[10:11]
	s_lshl_b64 s[30:31], s[24:25], 11
	s_lshl_b32 s5, s8, 4
	s_mul_i32 s6, s8, 24
	v_lshlrev_b32_e32 v78, 2, v2
	v_lshlrev_b32_e32 v80, 2, v4
	v_lshlrev_b32_e32 v82, 2, v6
	v_lshlrev_b32_e32 v84, 2, v8
	v_and_b32_e32 v223, 63, v166
	v_lshlrev_b32_e32 v223, 4, v223
	v_add_u32_e32 v248, 0x12000, v223
	v_mov_b32_e32 v242, 0x2000000
	v_mov_b32_e32 v243, 0
	v_lshrrev_b32_e32 v249, 6, v166
	v_lshlrev_b32_e32 v249, 11, v249
	v_add_u32_e32 v249, v249, v223
	v_add_u32_e32 v249, 0x13000, v249
	v_lshlrev_b32_e32 v50, 4, v166
	s_mov_b64 s[98:99], s[44:45]
	global_load_dwordx4 v[10:13], v50, s[98:99]
	s_add_u32 s98, s98, 0x6000
	s_addc_u32 s99, s99, 0
	global_load_dwordx4 v[14:17], v50, s[98:99]
	s_add_u32 s98, s98, 0x6000
	s_addc_u32 s99, s99, 0
	global_load_dwordx4 v[18:21], v50, s[98:99]
	s_add_u32 s98, s98, 0x6000
	s_addc_u32 s99, s99, 0
	global_load_dwordx4 v[22:25], v50, s[98:99]
	s_add_u32 s98, s98, 0x6000
	s_addc_u32 s99, s99, 0
	global_load_dwordx4 v[26:29], v50, s[98:99]
	s_add_u32 s98, s98, 0x6000
	s_addc_u32 s99, s99, 0
	global_load_dwordx4 v[30:33], v50, s[98:99]
	s_add_u32 s98, s98, 0x6000
	s_addc_u32 s99, s99, 0
	global_load_dwordx4 v[34:37], v50, s[98:99]
	s_add_u32 s98, s98, 0x6000
	s_addc_u32 s99, s99, 0
	global_load_dwordx4 v[38:41], v50, s[98:99]
	s_add_u32 s98, s98, 0x6000
	s_addc_u32 s99, s99, 0
	global_load_dwordx4 v[42:45], v50, s[98:99]
	s_add_u32 s98, s98, 0x6000
	s_addc_u32 s99, s99, 0
	v_lshrrev_b32_e32 v54, 6, v166
	v_lshlrev_b32_e32 v54, 10, v54
	v_mov_b32_e32 v55, 0
	v_lshl_add_u64 v[52:53], v[70:71], 0, v[54:55]
	v_add_u32_e32 v51, 0x12000, v50
	v_cmp_gt_u32_e32 vcc, 0x100, v166
	s_and_saveexec_b64 s[98:99], vcc
	global_load_dwordx4 v[46:49], v[52:53], off
	s_waitcnt vmcnt(0)
	ds_write_b128 v51, v[46:49]
	s_mov_b64 exec, s[98:99]
	ds_write_b128 v50, v[10:13]
	v_add_u32_e32 v50, 0x2000, v50
	ds_write_b128 v50, v[14:17]
	v_add_u32_e32 v50, 0x2000, v50
	ds_write_b128 v50, v[18:21]
	v_add_u32_e32 v50, 0x2000, v50
	ds_write_b128 v50, v[22:25]
	v_add_u32_e32 v50, 0x2000, v50
	ds_write_b128 v50, v[26:29]
	v_add_u32_e32 v50, 0x2000, v50
	ds_write_b128 v50, v[30:33]
	v_add_u32_e32 v50, 0x2000, v50
	ds_write_b128 v50, v[34:37]
	v_add_u32_e32 v50, 0x2000, v50
	ds_write_b128 v50, v[38:41]
	v_add_u32_e32 v50, 0x2000, v50
	ds_write_b128 v50, v[42:45]
	s_waitcnt lgkmcnt(0)
	s_barrier
	s_branch .LBB0_530

.LBB0_530:
	v_add_u32_e32 v0, 0xffff8000, v66
	v_cmp_gt_i32_e32 vcc, s40, v66
	v_mov_b32_e32 v4, s55
	v_mov_b32_e32 v5, s48
	v_cndmask_b32_e32 v3, 0, v67, vcc
	v_cndmask_b32_e32 v2, v0, v66, vcc
	v_cndmask_b32_e32 v5, v4, v5, vcc
	v_mov_b32_e32 v4, s54
	v_mov_b32_e32 v6, s49
	v_cndmask_b32_e32 v4, v4, v6, vcc
	v_lshlrev_b64 v[2:3], 12, v[2:3]
	v_lshl_add_u64 v[2:3], v[4:5], 0, v[2:3]
	v_mov_b32_e32 v79, v1
	v_lshl_add_u64 v[2:3], v[2:3], 0, v[78:79]
	v_lshl_add_u64 v[212:213], v[2:3], 0, v[242:243]
	v_readfirstlane_b32 s98, v66
	s_sub_i32 s99, s98, 0x2000
	s_cmp_lt_u32 s99, 0x4800
	s_cbranch_scc0 .Lnp_2_0_ld
	s_waitcnt vmcnt(0)
	v_mov_b64_e32 v[38:39], v[122:123]
	v_mov_b64_e32 v[40:41], v[124:125]
	v_mov_b64_e32 v[22:23], v[126:127]
	v_mov_b64_e32 v[24:25], v[128:129]
	v_mov_b64_e32 v[6:7], v[130:131]
	v_mov_b64_e32 v[8:9], v[132:133]
	v_mov_b64_e32 v[2:3], v[134:135]
	v_mov_b64_e32 v[4:5], v[136:137]
	s_branch .Lnp_2_0_pf
.Lnp_2_0_ld:
	global_load_dwordx4 v[38:41], v[2:3], off nt
	global_load_dwordx4 v[22:25], v[2:3], off offset:1024 nt
	global_load_dwordx4 v[6:9], v[2:3], off offset:2048 nt
	global_load_dwordx4 v[2:5], v[2:3], off offset:3072 nt

.Lnp_2_0_dn:
	v_cmp_lt_i32_e32 vcc, s14, v66
	s_and_b64 s[8:9], s[22:23], vcc
	s_and_saveexec_b64 s[34:35], s[8:9]
	s_cbranch_execz .LBB0_532
	v_readlane_b32 s8, v253, 18
	v_lshlrev_b64 v[34:35], 12, v[0:1]
	v_readlane_b32 s9, v253, 19
	v_mov_b32_e32 v81, v1
	v_lshl_add_u64 v[62:63], v[72:73], 0, v[34:35]
	v_lshl_add_u64 v[10:11], s[8:9], 0, v[34:35]
	s_mov_b64 s[8:9], 0x800000
	v_lshl_add_u64 v[54:55], v[10:11], 0, s[8:9]
	s_mov_b64 s[8:9], 0x1000000
	v_lshl_add_u64 v[56:57], v[10:11], 0, s[8:9]
	s_mov_b64 s[8:9], 0x1800000
	v_lshl_add_u64 v[60:61], v[10:11], 0, v[78:79]
	v_lshl_add_u64 v[14:15], v[54:55], 0, v[78:79]
	v_lshl_add_u64 v[58:59], v[10:11], 0, s[8:9]
	global_load_dwordx4 v[10:13], v[60:61], off
	v_lshl_add_u64 v[18:19], v[56:57], 0, v[78:79]
	global_load_dwordx4 v[14:17], v[14:15], off
	v_lshl_add_u64 v[26:27], v[58:59], 0, v[78:79]
	global_load_dwordx4 v[18:21], v[18:19], off
	s_nop 0
	global_load_dwordx4 v[26:29], v[26:27], off
	s_nop 0
	global_load_dwordx4 v[30:33], v[68:69], off
	global_load_dwordx4 v[34:37], v[60:61], off offset:1024
	v_lshl_add_u64 v[42:43], v[54:55], 0, v[80:81]
	v_lshl_add_u64 v[46:47], v[56:57], 0, v[80:81]
	v_lshl_add_u64 v[50:51], v[58:59], 0, v[80:81]
	global_load_dwordx4 v[42:45], v[42:43], off
	s_nop 0
	global_load_dwordx4 v[46:49], v[46:47], off
	s_nop 0
	global_load_dwordx4 v[50:53], v[50:51], off
	v_mov_b32_e32 v83, v1
	v_mov_b32_e32 v85, v1
	s_waitcnt vmcnt(0)
	v_pk_add_f32 v[12:13], v[12:13], v[16:17]
	v_pk_add_f32 v[10:11], v[10:11], v[14:15]
	v_pk_add_f32 v[12:13], v[12:13], v[20:21]
	v_pk_add_f32 v[10:11], v[10:11], v[18:19]
	v_pk_add_f32 v[12:13], v[12:13], v[28:29]
	v_pk_add_f32 v[10:11], v[10:11], v[26:27]
	v_pk_fma_f32 v[40:41], v[12:13], v[32:33], v[40:41]
	v_pk_fma_f32 v[38:39], v[10:11], v[30:31], v[38:39]
	global_store_dwordx4 v[62:63], v[38:41], off
	global_load_dwordx4 v[10:13], v[68:69], off offset:1024
	v_pk_add_f32 v[36:37], v[36:37], v[44:45]
	v_pk_add_f32 v[34:35], v[34:35], v[42:43]
	v_pk_add_f32 v[36:37], v[36:37], v[48:49]
	v_pk_add_f32 v[34:35], v[34:35], v[46:47]
	global_load_dwordx4 v[14:17], v[60:61], off offset:2048
	v_pk_add_f32 v[36:37], v[36:37], v[52:53]
	v_pk_add_f32 v[34:35], v[34:35], v[50:51]
	v_lshl_add_u64 v[18:19], v[54:55], 0, v[82:83]
	v_lshl_add_u64 v[26:27], v[56:57], 0, v[82:83]
	v_lshl_add_u64 v[30:31], v[58:59], 0, v[82:83]
	global_load_dwordx4 v[18:21], v[18:19], off
	s_nop 0
	global_load_dwordx4 v[26:29], v[26:27], off
	s_nop 0
	global_load_dwordx4 v[30:33], v[30:31], off
	v_lshl_add_u64 v[42:43], v[54:55], 0, v[84:85]
	v_lshl_add_u64 v[46:47], v[56:57], 0, v[84:85]
	v_lshl_add_u64 v[50:51], v[58:59], 0, v[84:85]
	s_waitcnt vmcnt(4)
	v_pk_fma_f32 v[24:25], v[36:37], v[12:13], v[24:25]
	v_pk_fma_f32 v[22:23], v[34:35], v[10:11], v[22:23]
	global_store_dwordx4 v[62:63], v[22:25], off offset:1024
	global_load_dwordx4 v[10:13], v[68:69], off offset:2048
	global_load_dwordx4 v[34:37], v[60:61], off offset:3072
	s_nop 0
	global_load_dwordx4 v[42:45], v[42:43], off
	s_nop 0
	global_load_dwordx4 v[46:49], v[46:47], off
	s_nop 0
	global_load_dwordx4 v[50:53], v[50:51], off
	s_waitcnt vmcnt(8)
	v_pk_add_f32 v[16:17], v[16:17], v[20:21]
	v_pk_add_f32 v[14:15], v[14:15], v[18:19]
	s_waitcnt vmcnt(7)
	v_pk_add_f32 v[16:17], v[16:17], v[28:29]
	v_pk_add_f32 v[14:15], v[14:15], v[26:27]
	s_waitcnt vmcnt(6)
	v_pk_add_f32 v[16:17], v[16:17], v[32:33]
	v_pk_add_f32 v[14:15], v[14:15], v[30:31]
	s_waitcnt vmcnt(4)
	v_pk_fma_f32 v[8:9], v[16:17], v[12:13], v[8:9]
	v_pk_fma_f32 v[6:7], v[14:15], v[10:11], v[6:7]
	global_store_dwordx4 v[62:63], v[6:9], off offset:2048
	global_load_dwordx4 v[10:13], v[68:69], off offset:3072
	s_waitcnt vmcnt(4)
	v_pk_add_f32 v[14:15], v[36:37], v[44:45]
	v_pk_add_f32 v[16:17], v[34:35], v[42:43]
	s_waitcnt vmcnt(3)
	v_pk_add_f32 v[14:15], v[14:15], v[48:49]
	v_pk_add_f32 v[16:17], v[16:17], v[46:47]
	s_waitcnt vmcnt(2)
	v_pk_add_f32 v[14:15], v[14:15], v[52:53]
	v_pk_add_f32 v[16:17], v[16:17], v[50:51]
	s_waitcnt vmcnt(0)
	v_pk_fma_f32 v[4:5], v[14:15], v[12:13], v[4:5]
	v_pk_fma_f32 v[2:3], v[16:17], v[10:11], v[2:3]
	global_store_dwordx4 v[62:63], v[2:5], off offset:3072
.LBB0_532:
	s_or_b64 exec, exec, s[34:35]
	v_add_u32_e32 v86, s4, v66
	v_min_i32_e32 v10, 0x87ff, v86
	v_ashrrev_i32_e32 v11, 31, v10
	v_add_u32_e32 v0, 0xffff8000, v10
	v_cmp_gt_i32_e32 vcc, s40, v86
	v_mov_b32_e32 v12, s55
	v_mov_b32_e32 v13, s48
	v_cndmask_b32_e32 v11, 0, v11, vcc
	v_cndmask_b32_e32 v10, v0, v10, vcc
	v_cndmask_b32_e32 v13, v12, v13, vcc
	v_mov_b32_e32 v12, s54
	v_mov_b32_e32 v14, s49
	v_cndmask_b32_e32 v12, v12, v14, vcc
	v_lshlrev_b64 v[10:11], 12, v[10:11]
	v_lshl_add_u64 v[10:11], v[12:13], 0, v[10:11]
	v_lshl_add_u64 v[10:11], v[10:11], 0, v[78:79]
	v_lshl_add_u64 v[212:213], v[10:11], 0, v[242:243]
	v_readfirstlane_b32 s98, v66
	s_sub_i32 s99, s98, 0x2000
	s_cmp_lt_u32 s99, 0x4800
	s_cbranch_scc0 .Lnp_2_1_ld
	v_mov_b64_e32 v[34:35], v[138:139]
	v_mov_b64_e32 v[36:37], v[140:141]
	v_mov_b64_e32 v[30:31], v[142:143]
	v_mov_b64_e32 v[32:33], v[144:145]
	v_mov_b64_e32 v[18:19], v[146:147]
	v_mov_b64_e32 v[20:21], v[148:149]
	v_mov_b64_e32 v[10:11], v[150:151]
	v_mov_b64_e32 v[12:13], v[152:153]
	s_branch .Lnp_2_1_pf
.Lnp_2_1_ld:
	global_load_dwordx4 v[34:37], v[10:11], off nt
	global_load_dwordx4 v[30:33], v[10:11], off offset:1024 nt
	global_load_dwordx4 v[18:21], v[10:11], off offset:2048 nt
	global_load_dwordx4 v[10:13], v[10:11], off offset:3072 nt

.Lnp_2_1_dn:
	v_cmp_lt_i32_e32 vcc, s14, v86
	s_mov_b32 s8, 0x8800
	v_cmp_gt_i32_e64 s[8:9], s8, v86
	s_and_b64 vcc, vcc, s[8:9]
	s_and_b64 s[8:9], s[22:23], vcc
	s_and_saveexec_b64 s[34:35], s[8:9]
	s_cbranch_execz .LBB0_542
	v_readlane_b32 s8, v253, 18
	v_lshlrev_b64 v[14:15], 12, v[0:1]
	v_readlane_b32 s9, v253, 19
	v_mov_b32_e32 v79, v1
	v_cmp_gt_u32_e32 vcc, s15, v86
	v_lshl_add_u64 v[42:43], s[8:9], 0, v[14:15]
	s_mov_b64 s[8:9], 0x800000
	v_lshl_add_u64 v[28:29], v[42:43], 0, s[8:9]
	s_mov_b64 s[8:9], 0x1000000
	v_lshl_add_u64 v[26:27], v[42:43], 0, s[8:9]
	s_mov_b64 s[8:9], 0x1800000
	v_lshl_add_u64 v[16:17], v[42:43], 0, s[8:9]
	v_lshl_add_u64 v[42:43], v[42:43], 0, v[78:79]
	v_lshl_add_u64 v[28:29], v[28:29], 0, v[78:79]
	v_lshl_add_u64 v[26:27], v[26:27], 0, v[78:79]
	v_lshl_add_u64 v[16:17], v[16:17], 0, v[78:79]
	v_lshl_add_u64 v[14:15], s[54:55], 0, v[14:15]
	v_lshl_add_u64 v[44:45], v[14:15], 0, v[78:79]
	global_load_dwordx4 v[118:121], v[42:43], off
	global_load_dwordx4 v[122:125], v[28:29], off
	global_load_dwordx4 v[126:129], v[26:27], off
	global_load_dwordx4 v[130:133], v[16:17], off
	global_load_dwordx4 v[204:207], v[68:69], off
	global_load_dwordx4 v[134:137], v[42:43], off offset:1024
	global_load_dwordx4 v[138:141], v[28:29], off offset:1024
	global_load_dwordx4 v[142:145], v[26:27], off offset:1024
	global_load_dwordx4 v[146:149], v[16:17], off offset:1024
	global_load_dwordx4 v[208:211], v[68:69], off offset:1024
	global_load_dwordx4 v[150:153], v[42:43], off offset:2048
	global_load_dwordx4 v[176:179], v[28:29], off offset:2048
	global_load_dwordx4 v[180:183], v[26:27], off offset:2048
	global_load_dwordx4 v[184:187], v[16:17], off offset:2048
	global_load_dwordx4 v[88:91], v[68:69], off offset:2048
	global_load_dwordx4 v[188:191], v[42:43], off offset:3072
	global_load_dwordx4 v[192:195], v[28:29], off offset:3072
	global_load_dwordx4 v[196:199], v[26:27], off offset:3072
	global_load_dwordx4 v[200:203], v[16:17], off offset:3072
	global_load_dwordx4 v[92:95], v[68:69], off offset:3072
	s_waitcnt vmcnt(15)
	v_pk_add_f32 v[120:121], v[120:121], v[124:125]
	v_pk_add_f32 v[118:119], v[118:119], v[122:123]
	v_pk_add_f32 v[120:121], v[120:121], v[128:129]
	v_pk_add_f32 v[118:119], v[118:119], v[126:127]
	v_pk_add_f32 v[120:121], v[120:121], v[132:133]
	v_pk_add_f32 v[118:119], v[118:119], v[130:131]
	v_pk_fma_f32 v[36:37], v[120:121], v[206:207], v[36:37]
	v_pk_fma_f32 v[34:35], v[118:119], v[204:205], v[34:35]
	s_and_saveexec_b64 s[36:37], vcc
	global_store_dwordx4 v[44:45], v[34:37], off
	s_or_b64 exec, exec, s[36:37]
	s_waitcnt vmcnt(10)
	v_pk_add_f32 v[136:137], v[136:137], v[140:141]
	v_pk_add_f32 v[134:135], v[134:135], v[138:139]
	v_pk_add_f32 v[136:137], v[136:137], v[144:145]
	v_pk_add_f32 v[134:135], v[134:135], v[142:143]
	v_pk_add_f32 v[136:137], v[136:137], v[148:149]
	v_pk_add_f32 v[134:135], v[134:135], v[146:147]
	v_pk_fma_f32 v[32:33], v[136:137], v[210:211], v[32:33]
	v_pk_fma_f32 v[30:31], v[134:135], v[208:209], v[30:31]
	s_and_saveexec_b64 s[36:37], vcc
	global_store_dwordx4 v[44:45], v[30:33], off offset:1024
	s_or_b64 exec, exec, s[36:37]
	s_waitcnt vmcnt(5)
	v_pk_add_f32 v[152:153], v[152:153], v[178:179]
	v_pk_add_f32 v[150:151], v[150:151], v[176:177]
	v_pk_add_f32 v[152:153], v[152:153], v[182:183]
	v_pk_add_f32 v[150:151], v[150:151], v[180:181]
	v_pk_add_f32 v[152:153], v[152:153], v[186:187]
	v_pk_add_f32 v[150:151], v[150:151], v[184:185]
	v_pk_fma_f32 v[20:21], v[152:153], v[90:91], v[20:21]
	v_pk_fma_f32 v[18:19], v[150:151], v[88:89], v[18:19]
	s_and_saveexec_b64 s[36:37], vcc
	global_store_dwordx4 v[44:45], v[18:21], off offset:2048
	s_or_b64 exec, exec, s[36:37]
	s_waitcnt vmcnt(0)
	v_pk_add_f32 v[190:191], v[190:191], v[194:195]
	v_pk_add_f32 v[188:189], v[188:189], v[192:193]
	v_pk_add_f32 v[190:191], v[190:191], v[198:199]
	v_pk_add_f32 v[188:189], v[188:189], v[196:197]
	v_pk_add_f32 v[190:191], v[190:191], v[202:203]
	v_pk_add_f32 v[188:189], v[188:189], v[200:201]
	v_pk_fma_f32 v[12:13], v[190:191], v[94:95], v[12:13]
	v_pk_fma_f32 v[10:11], v[188:189], v[92:93], v[10:11]
	s_and_saveexec_b64 s[36:37], vcc
	global_store_dwordx4 v[44:45], v[10:13], off offset:3072
	s_or_b64 exec, exec, s[36:37]

.LBB0_542:
	s_or_b64 exec, exec, s[34:35]
	v_add_u32_e32 v88, s5, v66
	v_min_i32_e32 v14, 0x87ff, v88
	v_ashrrev_i32_e32 v15, 31, v14
	v_add_u32_e32 v0, 0xffff8000, v14
	v_cmp_gt_i32_e32 vcc, s40, v88
	v_mov_b32_e32 v16, s55
	v_mov_b32_e32 v17, s48
	v_cndmask_b32_e32 v15, 0, v15, vcc
	v_cndmask_b32_e32 v14, v0, v14, vcc
	v_cndmask_b32_e32 v17, v16, v17, vcc
	v_mov_b32_e32 v16, s54
	v_mov_b32_e32 v26, s49
	v_cndmask_b32_e32 v16, v16, v26, vcc
	v_lshlrev_b64 v[14:15], 12, v[14:15]
	v_lshl_add_u64 v[14:15], v[16:17], 0, v[14:15]
	v_mov_b32_e32 v79, v1
	v_lshl_add_u64 v[14:15], v[14:15], 0, v[78:79]
	v_lshl_add_u64 v[212:213], v[14:15], 0, v[242:243]
	v_readfirstlane_b32 s98, v66
	s_sub_i32 s99, s98, 0x2000
	s_cmp_lt_u32 s99, 0x4800
	s_cbranch_scc0 .Lnp_2_2_ld
	v_mov_b64_e32 v[46:47], v[204:205]
	v_mov_b64_e32 v[48:49], v[206:207]
	v_mov_b64_e32 v[42:43], v[208:209]
	v_mov_b64_e32 v[44:45], v[210:211]
	v_mov_b64_e32 v[26:27], v[224:225]
	v_mov_b64_e32 v[28:29], v[226:227]
	v_mov_b64_e32 v[14:15], v[234:235]
	v_mov_b64_e32 v[16:17], v[236:237]
	s_branch .Lnp_2_2_pf
.Lnp_2_2_ld:
	global_load_dwordx4 v[46:49], v[14:15], off nt
	global_load_dwordx4 v[42:45], v[14:15], off offset:1024 nt
	global_load_dwordx4 v[26:29], v[14:15], off offset:2048 nt
	global_load_dwordx4 v[14:17], v[14:15], off offset:3072 nt

.Lnp_2_2_dn:
	v_cmp_lt_i32_e32 vcc, s14, v88
	s_mov_b32 s8, 0x8800
	v_cmp_gt_i32_e64 s[8:9], s8, v88
	s_and_b64 vcc, vcc, s[8:9]
	s_and_b64 s[8:9], s[22:23], vcc
	s_and_saveexec_b64 s[34:35], s[8:9]
	s_cbranch_execz .LBB0_552
	v_readlane_b32 s8, v253, 18
	v_lshlrev_b64 v[50:51], 12, v[0:1]
	v_readlane_b32 s9, v253, 19
	v_cmp_gt_u32_e32 vcc, s15, v88
	s_nop 0
	v_lshl_add_u64 v[58:59], s[8:9], 0, v[50:51]
	s_mov_b64 s[8:9], 0x800000
	v_lshl_add_u64 v[56:57], v[58:59], 0, s[8:9]
	s_mov_b64 s[8:9], 0x1000000
	v_lshl_add_u64 v[54:55], v[58:59], 0, s[8:9]
	s_mov_b64 s[8:9], 0x1800000
	v_lshl_add_u64 v[52:53], v[58:59], 0, s[8:9]
	v_lshl_add_u64 v[58:59], v[58:59], 0, v[78:79]
	v_lshl_add_u64 v[64:65], v[56:57], 0, v[78:79]
	global_load_dwordx4 v[60:63], v[58:59], off
	global_load_dwordx4 v[90:93], v[64:65], off
	v_lshl_add_u64 v[50:51], s[54:55], 0, v[50:51]
	s_waitcnt vmcnt(0)
	v_pk_add_f32 v[90:91], v[60:61], v[90:91]
	v_lshl_add_u64 v[60:61], v[54:55], 0, v[78:79]
	v_pk_add_f32 v[64:65], v[62:63], v[92:93]
	global_load_dwordx4 v[60:63], v[60:61], off
	s_waitcnt vmcnt(0)
	v_pk_add_f32 v[90:91], v[90:91], v[60:61]
	v_lshl_add_u64 v[60:61], v[52:53], 0, v[78:79]
	v_pk_add_f32 v[64:65], v[64:65], v[62:63]
	global_load_dwordx4 v[60:63], v[60:61], off
	s_waitcnt vmcnt(0)
	v_pk_add_f32 v[64:65], v[64:65], v[62:63]
	v_pk_add_f32 v[90:91], v[90:91], v[60:61]
	global_load_dwordx4 v[60:63], v[68:69], off
	s_waitcnt vmcnt(0)
	v_pk_fma_f32 v[48:49], v[64:65], v[62:63], v[48:49]
	v_pk_fma_f32 v[46:47], v[90:91], v[60:61], v[46:47]
	s_and_saveexec_b64 s[36:37], vcc
	s_cbranch_execz .LBB0_545
	v_mov_b32_e32 v79, v1
	v_lshl_add_u64 v[60:61], v[50:51], 0, v[78:79]
	global_store_dwordx4 v[60:61], v[46:49], off

.LBB0_552:
	s_or_b64 exec, exec, s[34:35]
	v_add_u32_e32 v90, s6, v66
	v_min_i32_e32 v50, 0x87ff, v90
	v_ashrrev_i32_e32 v51, 31, v50
	v_add_u32_e32 v0, 0xffff8000, v50
	v_cmp_gt_i32_e32 vcc, s40, v90
	v_mov_b32_e32 v52, s55
	v_mov_b32_e32 v53, s48
	v_cndmask_b32_e32 v51, 0, v51, vcc
	v_cndmask_b32_e32 v50, v0, v50, vcc
	v_cndmask_b32_e32 v53, v52, v53, vcc
	v_mov_b32_e32 v52, s54
	v_mov_b32_e32 v54, s49
	v_cndmask_b32_e32 v52, v52, v54, vcc
	v_lshlrev_b64 v[50:51], 12, v[50:51]
	v_lshl_add_u64 v[50:51], v[52:53], 0, v[50:51]
	v_mov_b32_e32 v79, v1
	v_lshl_add_u64 v[50:51], v[50:51], 0, v[78:79]
	v_lshl_add_u64 v[212:213], v[50:51], 0, v[242:243]
	v_readfirstlane_b32 s98, v66
	s_sub_i32 s99, s98, 0x2000
	s_cmp_lt_u32 s99, 0x4800
	s_cbranch_scc0 .Lnp_2_3_ld
	v_mov_b64_e32 v[62:63], v[238:239]
	v_mov_b64_e32 v[64:65], v[240:241]
	v_mov_b64_e32 v[58:59], v[244:245]
	v_mov_b64_e32 v[60:61], v[246:247]
	ds_read_b128 v[54:57], v249
	ds_read_b128 v[50:53], v249 offset:1024
	s_branch .Lnp_2_3_pf
.Lnp_2_3_ld:
	global_load_dwordx4 v[62:65], v[50:51], off nt
	global_load_dwordx4 v[58:61], v[50:51], off offset:1024 nt
	global_load_dwordx4 v[54:57], v[50:51], off offset:2048 nt
	global_load_dwordx4 v[50:53], v[50:51], off offset:3072 nt

.Lnp_2_3_dn:
	v_cmp_lt_i32_e32 vcc, s14, v90
	s_mov_b32 s8, 0x8800
	v_cmp_gt_i32_e64 s[8:9], s8, v90
	s_and_b64 vcc, vcc, s[8:9]
	s_and_b64 s[8:9], s[22:23], vcc
	s_and_saveexec_b64 s[34:35], s[8:9]
	s_cbranch_execz .LBB0_562
	v_readlane_b32 s8, v253, 18
	v_lshlrev_b64 v[92:93], 12, v[0:1]
	v_readlane_b32 s9, v253, 19
	v_cmp_gt_u32_e32 vcc, s15, v90
	s_nop 0
	v_lshl_add_u64 v[100:101], s[8:9], 0, v[92:93]
	s_mov_b64 s[8:9], 0x800000
	v_lshl_add_u64 v[98:99], v[100:101], 0, s[8:9]
	s_mov_b64 s[8:9], 0x1000000
	v_lshl_add_u64 v[96:97], v[100:101], 0, s[8:9]
	s_mov_b64 s[8:9], 0x1800000
	v_lshl_add_u64 v[94:95], v[100:101], 0, s[8:9]
	v_lshl_add_u64 v[100:101], v[100:101], 0, v[78:79]
	v_lshl_add_u64 v[112:113], v[98:99], 0, v[78:79]
	global_load_dwordx4 v[108:111], v[100:101], off
	s_nop 0
	global_load_dwordx4 v[112:115], v[112:113], off
	v_lshl_add_u64 v[116:117], v[96:97], 0, v[78:79]
	global_load_dwordx4 v[116:119], v[116:117], off
	v_lshl_add_u64 v[120:121], v[94:95], 0, v[78:79]
	global_load_dwordx4 v[120:123], v[120:121], off
	s_nop 0
	global_load_dwordx4 v[124:127], v[68:69], off
	v_lshl_add_u64 v[92:93], s[54:55], 0, v[92:93]
	s_waitcnt vmcnt(0)
	v_pk_add_f32 v[110:111], v[110:111], v[114:115]
	v_pk_add_f32 v[108:109], v[108:109], v[112:113]
	v_pk_add_f32 v[110:111], v[110:111], v[118:119]
	v_pk_add_f32 v[108:109], v[108:109], v[116:117]
	v_pk_add_f32 v[110:111], v[110:111], v[122:123]
	v_pk_add_f32 v[108:109], v[108:109], v[120:121]
	v_pk_fma_f32 v[64:65], v[110:111], v[126:127], v[64:65]
	v_pk_fma_f32 v[62:63], v[108:109], v[124:125], v[62:63]
	s_and_saveexec_b64 s[36:37], vcc
	s_cbranch_execz .LBB0_555
	v_mov_b32_e32 v79, v1
	v_lshl_add_u64 v[108:109], v[92:93], 0, v[78:79]
	global_store_dwordx4 v[108:109], v[62:65], off

.LBB0_562:
	s_or_b64 exec, exec, s[34:35]
	v_min_i32_e32 v0, 0x8000, v66
	v_ashrrev_i32_e32 v0, 12, v0
	v_lshl_add_u32 v222, v0, 13, v223
	v_mul_i32_i24_e32 v92, 0x1800, v0
	v_ashrrev_i32_e32 v93, 31, v92
	v_lshl_add_u64 v[100:101], v[92:93], 2, s[44:45]
	s_mov_b64 s[8:9], 0x1000
	v_lshl_add_u64 v[112:113], v[100:101], 0, s[8:9]
	v_mov_b32_e32 v79, v1
	v_lshl_add_u64 v[96:97], v[112:113], 0, v[78:79]
	ds_read_b128 v[92:95], v248
	v_lshl_add_u64 v[100:101], v[100:101], 0, v[78:79]
	ds_read_b128 v[96:99], v222 offset:4096
	v_readfirstlane_b32 s98, v66
	s_cmp_lt_u32 s98, 0x2000
	s_cbranch_scc0 .Lnp_2x_w1
	s_waitcnt vmcnt(4)
	s_branch .Lnp_2x_wd

.Lnp_2x_wd:
	s_waitcnt lgkmcnt(0)
	v_mul_f32_e32 v0, v39, v39
	ds_read_b128 v[108:111], v222
	v_mov_b32_e32 v81, v1
	v_mov_b32_e32 v83, v1
	v_mov_b32_e32 v85, v1
	ds_read_b128 v[168:171], v248 offset:1024
	v_lshl_add_u64 v[172:173], v[112:113], 0, v[80:81]
	ds_read_b128 v[172:175], v222 offset:5120
	ds_read_b128 v[176:179], v222 offset:1024
	ds_read_b128 v[180:183], v248 offset:2048
	v_lshl_add_u64 v[184:185], v[112:113], 0, v[82:83]
	ds_read_b128 v[184:187], v222 offset:6144
	ds_read_b128 v[188:191], v222 offset:2048
	ds_read_b128 v[192:195], v248 offset:3072
	v_lshl_add_u64 v[196:197], v[112:113], 0, v[84:85]
	ds_read_b128 v[196:199], v222 offset:7168
	ds_read_b128 v[200:203], v222 offset:3072
	v_mul_f32_e32 v81, v23, v23
	v_mul_f32_e32 v83, v7, v7
	v_fmac_f32_e32 v0, v38, v38
	v_fmac_f32_e32 v81, v22, v22
	v_mul_f32_e32 v85, v3, v3
	v_fmac_f32_e32 v83, v6, v6
	v_fmac_f32_e32 v0, v40, v40
	v_fmac_f32_e32 v81, v24, v24
	v_fmac_f32_e32 v85, v2, v2
	v_fmac_f32_e32 v83, v8, v8
	v_fmac_f32_e32 v0, v41, v41
	v_fmac_f32_e32 v81, v25, v25
	v_fmac_f32_e32 v85, v4, v4
	v_fmac_f32_e32 v83, v9, v9
	v_add_f32_e32 v0, v81, v0
	v_fmac_f32_e32 v85, v5, v5
	v_add_f32_e32 v0, v83, v0
	v_add_f32_e32 v0, v85, v0
	ds_bpermute_b32 v81, v102, v0
	v_mov_b32_e32 v85, v1
	s_waitcnt lgkmcnt(0)
	v_add_f32_e32 v0, v0, v81
	ds_bpermute_b32 v81, v103, v0
	s_waitcnt lgkmcnt(0)
	v_add_f32_e32 v0, v0, v81
	ds_bpermute_b32 v81, v104, v0
	s_waitcnt lgkmcnt(0)
	v_add_f32_e32 v0, v0, v81
	ds_bpermute_b32 v81, v105, v0
	s_waitcnt lgkmcnt(0)
	v_add_f32_e32 v0, v0, v81
	ds_bpermute_b32 v81, v106, v0
	s_waitcnt lgkmcnt(0)
	v_add_f32_e32 v0, v0, v81
	ds_bpermute_b32 v81, v107, v0
	s_waitcnt lgkmcnt(0)
	v_add_f32_e32 v0, v0, v81
	v_fmamk_f32 v0, v0, 0x3a800000, v218
	v_mul_f32_e32 v81, 0x4b800000, v0
	v_cmp_gt_f32_e32 vcc, s13, v0
	s_nop 1
	v_cndmask_b32_e32 v0, v0, v81, vcc
	v_rsq_f32_e32 v0, v0
	v_mov_b32_e32 v81, v1
	v_mul_f32_e32 v83, 0x45800000, v0
	v_cndmask_b32_e32 v0, v0, v83, vcc
	v_pk_mul_f32 v[40:41], v[40:41], v[0:1] op_sel_hi:[1,0]
	v_pk_mul_f32 v[38:39], v[38:39], v[0:1] op_sel_hi:[1,0]
	v_pk_mul_f32 v[24:25], v[24:25], v[0:1] op_sel_hi:[1,0]
	v_pk_mul_f32 v[22:23], v[22:23], v[0:1] op_sel_hi:[1,0]
	v_mov_b32_e32 v83, v1
	v_pk_mul_f32 v[8:9], v[8:9], v[0:1] op_sel_hi:[1,0]
	v_pk_mul_f32 v[6:7], v[6:7], v[0:1] op_sel_hi:[1,0]
	v_pk_mul_f32 v[4:5], v[4:5], v[0:1] op_sel_hi:[1,0]
	v_pk_mul_f32 v[2:3], v[2:3], v[0:1] op_sel_hi:[1,0]
	v_pk_mul_f32 v[38:39], v[92:93], v[38:39]
	v_pk_mul_f32 v[40:41], v[94:95], v[40:41]
	v_pk_add_f32 v[92:93], v[98:99], 1.0 op_sel_hi:[1,0]
	v_pk_add_f32 v[94:95], v[96:97], 1.0 op_sel_hi:[1,0]
	s_waitcnt lgkmcnt(0)
	v_pk_fma_f32 v[40:41], v[92:93], v[40:41], v[110:111]
	v_pk_fma_f32 v[38:39], v[94:95], v[38:39], v[108:109]
	v_lshl_add_u64 v[92:93], v[112:113], 0, v[80:81]
	v_cvt_pk_bf16_f32 v38, v38, v39
	v_cvt_pk_bf16_f32 v39, v40, v41
	global_store_dwordx2 v[76:77], v[38:39], off
	v_cmp_gt_i32_e32 vcc, s15, v86
	s_waitcnt lgkmcnt(0)
	v_pk_mul_f32 v[22:23], v[168:169], v[22:23]
	v_pk_mul_f32 v[24:25], v[170:171], v[24:25]
	v_pk_add_f32 v[38:39], v[174:175], 1.0 op_sel_hi:[1, 0]
	v_pk_add_f32 v[40:41], v[172:173], 1.0 op_sel_hi:[1, 0]
	v_pk_fma_f32 v[24:25], v[38:39], v[24:25], v[178:179]
	v_pk_fma_f32 v[22:23], v[40:41], v[22:23], v[176:177]
	v_lshl_add_u64 v[38:39], v[112:113], 0, v[82:83]
	v_cvt_pk_bf16_f32 v22, v22, v23
	v_cvt_pk_bf16_f32 v23, v24, v25
	global_store_dwordx2 v[76:77], v[22:23], off offset:512
	s_waitcnt lgkmcnt(0)
	v_pk_mul_f32 v[6:7], v[180:181], v[6:7]
	v_pk_mul_f32 v[8:9], v[182:183], v[8:9]
	v_pk_add_f32 v[22:23], v[186:187], 1.0 op_sel_hi:[1, 0]
	v_pk_add_f32 v[24:25], v[184:185], 1.0 op_sel_hi:[1, 0]
	v_pk_fma_f32 v[8:9], v[22:23], v[8:9], v[190:191]
	v_pk_fma_f32 v[6:7], v[24:25], v[6:7], v[188:189]
	v_lshl_add_u64 v[22:23], v[112:113], 0, v[84:85]
	v_cvt_pk_bf16_f32 v6, v6, v7
	v_cvt_pk_bf16_f32 v7, v8, v9
	global_store_dwordx2 v[76:77], v[6:7], off offset:1024
	s_waitcnt lgkmcnt(0)
	v_pk_mul_f32 v[2:3], v[2:3], v[192:193]
	v_pk_mul_f32 v[4:5], v[4:5], v[194:195]
	v_pk_add_f32 v[6:7], v[198:199], 1.0 op_sel_hi:[1, 0]
	v_pk_add_f32 v[8:9], v[196:197], 1.0 op_sel_hi:[1, 0]
	v_pk_fma_f32 v[4:5], v[4:5], v[6:7], v[202:203]
	v_pk_fma_f32 v[2:3], v[2:3], v[8:9], v[200:201]
	s_nop 0
	v_cvt_pk_bf16_f32 v2, v2, v3
	v_cvt_pk_bf16_f32 v3, v4, v5
	global_store_dwordx2 v[76:77], v[2:3], off offset:1536
	s_and_saveexec_b64 s[34:35], vcc
	s_cbranch_execz .LBB0_565
	v_min_i32_e32 v0, 0x8000, v86
	v_ashrrev_i32_e32 v0, 12, v0
	v_lshl_add_u32 v222, v0, 13, v223
	v_mul_i32_i24_e32 v2, 0x1800, v0
	v_ashrrev_i32_e32 v3, 31, v2
	v_lshl_add_u64 v[22:23], v[2:3], 2, s[44:45]
	v_lshl_add_u64 v[38:39], v[22:23], 0, s[8:9]
	v_lshl_add_u64 v[6:7], v[38:39], 0, v[78:79]
	ds_read_b128 v[2:5], v248
	v_lshl_add_u64 v[40:41], v[22:23], 0, v[78:79]
	ds_read_b128 v[6:9], v222 offset:4096
	v_mul_f32_e32 v0, v35, v35
	ds_read_b128 v[22:25], v222
	v_mov_b32_e32 v81, v1
	v_mov_b32_e32 v83, v1
	v_mov_b32_e32 v85, v1
	ds_read_b128 v[168:171], v248 offset:1024
	v_lshl_add_u64 v[172:173], v[38:39], 0, v[80:81]
	ds_read_b128 v[172:175], v222 offset:5120
	ds_read_b128 v[176:179], v222 offset:1024
	ds_read_b128 v[180:183], v248 offset:2048
	v_lshl_add_u64 v[184:185], v[38:39], 0, v[82:83]
	ds_read_b128 v[184:187], v222 offset:6144
	ds_read_b128 v[188:191], v222 offset:2048
	ds_read_b128 v[192:195], v248 offset:3072
	v_lshl_add_u64 v[196:197], v[38:39], 0, v[84:85]
	ds_read_b128 v[196:199], v222 offset:7168
	ds_read_b128 v[200:203], v222 offset:3072
	v_mul_f32_e32 v79, v31, v31
	v_mul_f32_e32 v87, v19, v19
	v_fmac_f32_e32 v0, v34, v34
	v_fmac_f32_e32 v79, v30, v30
	v_mul_f32_e32 v89, v11, v11
	v_fmac_f32_e32 v87, v18, v18
	v_fmac_f32_e32 v0, v36, v36
	v_fmac_f32_e32 v79, v32, v32
	v_fmac_f32_e32 v89, v10, v10
	v_fmac_f32_e32 v87, v20, v20
	v_fmac_f32_e32 v0, v37, v37
	v_fmac_f32_e32 v79, v33, v33
	v_fmac_f32_e32 v89, v12, v12
	v_fmac_f32_e32 v87, v21, v21
	v_add_f32_e32 v0, v79, v0
	v_fmac_f32_e32 v89, v13, v13
	v_add_f32_e32 v0, v87, v0
	v_add_f32_e32 v0, v89, v0
	ds_bpermute_b32 v79, v102, v0
	v_ashrrev_i32_e32 v87, 31, v86
	v_lshlrev_b64 v[86:87], 11, v[86:87]
	v_lshl_add_u64 v[86:87], v[74:75], 0, v[86:87]
	s_waitcnt lgkmcnt(0)
	v_add_f32_e32 v0, v0, v79
	ds_bpermute_b32 v79, v103, v0
	s_waitcnt lgkmcnt(0)
	v_add_f32_e32 v0, v0, v79
	ds_bpermute_b32 v79, v104, v0
	s_waitcnt lgkmcnt(0)
	v_add_f32_e32 v0, v0, v79
	ds_bpermute_b32 v79, v105, v0
	s_waitcnt lgkmcnt(0)
	v_add_f32_e32 v0, v0, v79
	ds_bpermute_b32 v79, v106, v0
	s_waitcnt lgkmcnt(0)
	v_add_f32_e32 v0, v0, v79
	ds_bpermute_b32 v79, v107, v0
	s_waitcnt lgkmcnt(0)
	v_add_f32_e32 v0, v0, v79
	v_fmamk_f32 v0, v0, 0x3a800000, v218
	v_mul_f32_e32 v79, 0x4b800000, v0
	v_cmp_gt_f32_e32 vcc, s13, v0
	s_waitcnt lgkmcnt(0)
	v_pk_add_f32 v[8:9], v[8:9], 1.0 op_sel_hi:[1,0]
	v_cndmask_b32_e32 v0, v0, v79, vcc
	v_rsq_f32_e32 v0, v0
	v_pk_add_f32 v[6:7], v[6:7], 1.0 op_sel_hi:[1,0]
	v_mul_f32_e32 v79, 0x45800000, v0
	v_cndmask_b32_e32 v0, v0, v79, vcc
	v_pk_mul_f32 v[36:37], v[36:37], v[0:1] op_sel_hi:[1,0]
	v_pk_mul_f32 v[34:35], v[34:35], v[0:1] op_sel_hi:[1,0]
	v_pk_mul_f32 v[4:5], v[4:5], v[36:37]
	v_pk_mul_f32 v[2:3], v[2:3], v[34:35]
	s_waitcnt lgkmcnt(0)
	v_pk_fma_f32 v[4:5], v[8:9], v[4:5], v[24:25]
	v_pk_fma_f32 v[2:3], v[6:7], v[2:3], v[22:23]
	v_lshl_add_u64 v[6:7], v[38:39], 0, v[80:81]
	v_cvt_pk_bf16_f32 v2, v2, v3
	v_cvt_pk_bf16_f32 v3, v4, v5
	global_store_dwordx2 v[86:87], v[2:3], off
	v_pk_mul_f32 v[32:33], v[32:33], v[0:1] op_sel_hi:[1,0]
	v_pk_mul_f32 v[30:31], v[30:31], v[0:1] op_sel_hi:[1,0]
	v_pk_mul_f32 v[20:21], v[20:21], v[0:1] op_sel_hi:[1,0]
	v_pk_mul_f32 v[18:19], v[18:19], v[0:1] op_sel_hi:[1,0]
	v_pk_mul_f32 v[12:13], v[12:13], v[0:1] op_sel_hi:[1,0]
	v_pk_mul_f32 v[10:11], v[10:11], v[0:1] op_sel_hi:[1,0]
	s_waitcnt lgkmcnt(0)
	v_pk_add_f32 v[8:9], v[174:175], 1.0 op_sel_hi:[1, 0]
	v_pk_mul_f32 v[2:3], v[168:169], v[30:31]
	v_pk_mul_f32 v[4:5], v[170:171], v[32:33]
	v_pk_add_f32 v[6:7], v[172:173], 1.0 op_sel_hi:[1, 0]
	v_pk_fma_f32 v[4:5], v[8:9], v[4:5], v[178:179]
	v_pk_fma_f32 v[2:3], v[6:7], v[2:3], v[176:177]
	v_lshl_add_u64 v[6:7], v[38:39], 0, v[82:83]
	v_cvt_pk_bf16_f32 v2, v2, v3
	v_cvt_pk_bf16_f32 v3, v4, v5
	global_store_dwordx2 v[86:87], v[2:3], off offset:512
	s_waitcnt lgkmcnt(0)
	v_pk_add_f32 v[8:9], v[186:187], 1.0 op_sel_hi:[1, 0]
	v_pk_mul_f32 v[2:3], v[180:181], v[18:19]
	v_pk_mul_f32 v[4:5], v[182:183], v[20:21]
	v_pk_add_f32 v[6:7], v[184:185], 1.0 op_sel_hi:[1, 0]
	v_pk_fma_f32 v[4:5], v[8:9], v[4:5], v[190:191]
	v_pk_fma_f32 v[2:3], v[6:7], v[2:3], v[188:189]
	v_lshl_add_u64 v[6:7], v[38:39], 0, v[84:85]
	v_cvt_pk_bf16_f32 v2, v2, v3
	v_cvt_pk_bf16_f32 v3, v4, v5
	global_store_dwordx2 v[86:87], v[2:3], off offset:1024
	s_waitcnt lgkmcnt(0)
	v_pk_add_f32 v[8:9], v[198:199], 1.0 op_sel_hi:[1, 0]
	v_pk_mul_f32 v[2:3], v[10:11], v[192:193]
	v_pk_mul_f32 v[4:5], v[12:13], v[194:195]
	v_pk_add_f32 v[6:7], v[196:197], 1.0 op_sel_hi:[1, 0]
	v_pk_fma_f32 v[4:5], v[4:5], v[8:9], v[202:203]
	v_pk_fma_f32 v[2:3], v[2:3], v[6:7], v[200:201]
	s_nop 0
	v_cvt_pk_bf16_f32 v2, v2, v3
	v_cvt_pk_bf16_f32 v3, v4, v5
	global_store_dwordx2 v[86:87], v[2:3], off offset:1536
	s_or_b64 exec, exec, s[34:35]
	v_cmp_gt_i32_e32 vcc, s15, v88
	s_and_saveexec_b64 s[34:35], vcc
	s_cbranch_execnz .LBB0_566

.LBB0_566:
	v_min_i32_e32 v0, 0x8000, v88
	v_ashrrev_i32_e32 v0, 12, v0
	v_lshl_add_u32 v222, v0, 13, v223
	v_mul_i32_i24_e32 v2, 0x1800, v0
	v_ashrrev_i32_e32 v3, 31, v2
	v_lshl_add_u64 v[10:11], v[2:3], 2, s[44:45]
	v_lshl_add_u64 v[18:19], v[10:11], 0, s[8:9]
	v_mov_b32_e32 v79, v1
	v_lshl_add_u64 v[6:7], v[18:19], 0, v[78:79]
	ds_read_b128 v[2:5], v248
	v_lshl_add_u64 v[20:21], v[10:11], 0, v[78:79]
	ds_read_b128 v[6:9], v222 offset:4096
	v_mul_f32_e32 v0, v47, v47
	ds_read_b128 v[10:13], v222
	v_mov_b32_e32 v81, v1
	v_mov_b32_e32 v83, v1
	v_mov_b32_e32 v85, v1
	ds_read_b128 v[168:171], v248 offset:1024
	v_lshl_add_u64 v[172:173], v[18:19], 0, v[80:81]
	ds_read_b128 v[172:175], v222 offset:5120
	ds_read_b128 v[176:179], v222 offset:1024
	ds_read_b128 v[180:183], v248 offset:2048
	v_lshl_add_u64 v[184:185], v[18:19], 0, v[82:83]
	ds_read_b128 v[184:187], v222 offset:6144
	ds_read_b128 v[188:191], v222 offset:2048
	ds_read_b128 v[192:195], v248 offset:3072
	v_lshl_add_u64 v[196:197], v[18:19], 0, v[84:85]
	ds_read_b128 v[196:199], v222 offset:7168
	ds_read_b128 v[200:203], v222 offset:3072
	v_mul_f32_e32 v22, v43, v43
	v_mul_f32_e32 v23, v27, v27
	v_fmac_f32_e32 v0, v46, v46
	v_fmac_f32_e32 v22, v42, v42
	v_mul_f32_e32 v24, v15, v15
	v_fmac_f32_e32 v23, v26, v26
	v_fmac_f32_e32 v0, v48, v48
	v_fmac_f32_e32 v22, v44, v44
	v_fmac_f32_e32 v24, v14, v14
	v_fmac_f32_e32 v23, v28, v28
	v_fmac_f32_e32 v0, v49, v49
	v_fmac_f32_e32 v22, v45, v45
	v_fmac_f32_e32 v24, v16, v16
	v_fmac_f32_e32 v23, v29, v29
	v_add_f32_e32 v0, v22, v0
	v_fmac_f32_e32 v24, v17, v17
	v_add_f32_e32 v0, v23, v0
	v_add_f32_e32 v0, v24, v0
	ds_bpermute_b32 v22, v102, v0
	v_ashrrev_i32_e32 v89, 31, v88
	v_mov_b32_e32 v81, v1
	v_mov_b32_e32 v83, v1
	v_mov_b32_e32 v85, v1
	s_waitcnt lgkmcnt(0)
	v_add_f32_e32 v0, v0, v22
	ds_bpermute_b32 v22, v103, v0
	s_waitcnt lgkmcnt(0)
	v_add_f32_e32 v0, v0, v22
	ds_bpermute_b32 v22, v104, v0
	s_waitcnt lgkmcnt(0)
	v_add_f32_e32 v0, v0, v22
	ds_bpermute_b32 v22, v105, v0
	s_waitcnt lgkmcnt(0)
	v_add_f32_e32 v0, v0, v22
	ds_bpermute_b32 v22, v106, v0
	s_waitcnt lgkmcnt(0)
	v_add_f32_e32 v0, v0, v22
	ds_bpermute_b32 v22, v107, v0
	s_waitcnt lgkmcnt(0)
	v_add_f32_e32 v0, v0, v22
	v_fmamk_f32 v0, v0, 0x3a800000, v218
	v_mul_f32_e32 v22, 0x4b800000, v0
	v_cmp_gt_f32_e32 vcc, s13, v0
	s_waitcnt lgkmcnt(0)
	v_pk_add_f32 v[8:9], v[8:9], 1.0 op_sel_hi:[1,0]
	v_cndmask_b32_e32 v0, v0, v22, vcc
	v_rsq_f32_e32 v0, v0
	v_pk_add_f32 v[6:7], v[6:7], 1.0 op_sel_hi:[1,0]
	v_lshlrev_b64 v[22:23], 11, v[88:89]
	v_lshl_add_u64 v[22:23], v[74:75], 0, v[22:23]
	v_mul_f32_e32 v24, 0x45800000, v0
	v_cndmask_b32_e32 v0, v0, v24, vcc
	v_pk_mul_f32 v[24:25], v[48:49], v[0:1] op_sel_hi:[1,0]
	v_pk_mul_f32 v[30:31], v[46:47], v[0:1] op_sel_hi:[1,0]
	v_pk_mul_f32 v[4:5], v[4:5], v[24:25]
	v_pk_mul_f32 v[2:3], v[2:3], v[30:31]
	s_waitcnt lgkmcnt(0)
	v_pk_fma_f32 v[4:5], v[8:9], v[4:5], v[12:13]
	v_pk_fma_f32 v[2:3], v[6:7], v[2:3], v[10:11]
	v_lshl_add_u64 v[6:7], v[18:19], 0, v[80:81]
	v_cvt_pk_bf16_f32 v2, v2, v3
	v_cvt_pk_bf16_f32 v3, v4, v5
	global_store_dwordx2 v[22:23], v[2:3], off
	v_pk_mul_f32 v[24:25], v[44:45], v[0:1] op_sel_hi:[1,0]
	v_pk_mul_f32 v[30:31], v[42:43], v[0:1] op_sel_hi:[1,0]
	v_pk_mul_f32 v[26:27], v[26:27], v[0:1] op_sel_hi:[1,0]
	v_pk_mul_f32 v[16:17], v[16:17], v[0:1] op_sel_hi:[1,0]
	v_pk_mul_f32 v[14:15], v[14:15], v[0:1] op_sel_hi:[1,0]
	s_waitcnt lgkmcnt(0)
	v_pk_add_f32 v[8:9], v[174:175], 1.0 op_sel_hi:[1, 0]
	v_pk_mul_f32 v[2:3], v[168:169], v[30:31]
	v_pk_mul_f32 v[4:5], v[170:171], v[24:25]
	v_pk_add_f32 v[6:7], v[172:173], 1.0 op_sel_hi:[1, 0]
	v_pk_fma_f32 v[4:5], v[8:9], v[4:5], v[178:179]
	v_pk_fma_f32 v[2:3], v[6:7], v[2:3], v[176:177]
	v_lshl_add_u64 v[6:7], v[18:19], 0, v[82:83]
	v_cvt_pk_bf16_f32 v2, v2, v3
	v_cvt_pk_bf16_f32 v3, v4, v5
	global_store_dwordx2 v[22:23], v[2:3], off offset:512
	v_pk_mul_f32 v[24:25], v[28:29], v[0:1] op_sel_hi:[1,0]
	s_waitcnt lgkmcnt(0)
	v_pk_add_f32 v[8:9], v[186:187], 1.0 op_sel_hi:[1, 0]
	v_pk_mul_f32 v[2:3], v[180:181], v[26:27]
	v_pk_mul_f32 v[4:5], v[182:183], v[24:25]
	v_pk_add_f32 v[6:7], v[184:185], 1.0 op_sel_hi:[1, 0]
	v_pk_fma_f32 v[4:5], v[8:9], v[4:5], v[190:191]
	v_pk_fma_f32 v[2:3], v[6:7], v[2:3], v[188:189]
	v_lshl_add_u64 v[6:7], v[18:19], 0, v[84:85]
	v_cvt_pk_bf16_f32 v2, v2, v3
	v_cvt_pk_bf16_f32 v3, v4, v5
	global_store_dwordx2 v[22:23], v[2:3], off offset:1024
	s_waitcnt lgkmcnt(0)
	v_pk_add_f32 v[8:9], v[198:199], 1.0 op_sel_hi:[1, 0]
	v_pk_mul_f32 v[2:3], v[14:15], v[192:193]
	v_pk_mul_f32 v[4:5], v[16:17], v[194:195]
	v_pk_add_f32 v[6:7], v[196:197], 1.0 op_sel_hi:[1, 0]
	v_pk_fma_f32 v[4:5], v[4:5], v[8:9], v[202:203]
	v_pk_fma_f32 v[2:3], v[2:3], v[6:7], v[200:201]
	s_nop 0
	v_cvt_pk_bf16_f32 v2, v2, v3
	v_cvt_pk_bf16_f32 v3, v4, v5
	global_store_dwordx2 v[22:23], v[2:3], off offset:1536
	s_or_b64 exec, exec, s[34:35]
	v_cmp_gt_i32_e32 vcc, s15, v90
	s_and_saveexec_b64 s[34:35], vcc
	s_cbranch_execz .LBB0_529
.LBB0_567:
	v_min_i32_e32 v0, 0x8000, v90
	v_ashrrev_i32_e32 v0, 12, v0
	v_lshl_add_u32 v222, v0, 13, v223
	v_mul_i32_i24_e32 v2, 0x1800, v0
	v_ashrrev_i32_e32 v3, 31, v2
	v_lshl_add_u64 v[10:11], v[2:3], 2, s[44:45]
	v_lshl_add_u64 v[14:15], v[10:11], 0, s[8:9]
	v_mov_b32_e32 v79, v1
	v_lshl_add_u64 v[6:7], v[14:15], 0, v[78:79]
	ds_read_b128 v[2:5], v248
	v_lshl_add_u64 v[16:17], v[10:11], 0, v[78:79]
	ds_read_b128 v[6:9], v222 offset:4096
	v_mul_f32_e32 v0, v63, v63
	ds_read_b128 v[10:13], v222
	v_mov_b32_e32 v81, v1
	v_mov_b32_e32 v83, v1
	v_mov_b32_e32 v85, v1
	ds_read_b128 v[168:171], v248 offset:1024
	v_lshl_add_u64 v[172:173], v[14:15], 0, v[80:81]
	ds_read_b128 v[172:175], v222 offset:5120
	ds_read_b128 v[176:179], v222 offset:1024
	ds_read_b128 v[180:183], v248 offset:2048
	v_lshl_add_u64 v[184:185], v[14:15], 0, v[82:83]
	ds_read_b128 v[184:187], v222 offset:6144
	ds_read_b128 v[188:191], v222 offset:2048
	ds_read_b128 v[192:195], v248 offset:3072
	v_lshl_add_u64 v[196:197], v[14:15], 0, v[84:85]
	ds_read_b128 v[196:199], v222 offset:7168
	ds_read_b128 v[200:203], v222 offset:3072
	v_mul_f32_e32 v18, v59, v59
	v_mul_f32_e32 v19, v55, v55
	v_fmac_f32_e32 v0, v62, v62
	v_fmac_f32_e32 v18, v58, v58
	v_mul_f32_e32 v20, v51, v51
	v_fmac_f32_e32 v19, v54, v54
	v_fmac_f32_e32 v0, v64, v64
	v_fmac_f32_e32 v18, v60, v60
	v_fmac_f32_e32 v20, v50, v50
	v_fmac_f32_e32 v19, v56, v56
	v_fmac_f32_e32 v0, v65, v65
	v_fmac_f32_e32 v18, v61, v61
	v_fmac_f32_e32 v20, v52, v52
	v_fmac_f32_e32 v19, v57, v57
	v_add_f32_e32 v0, v18, v0
	v_fmac_f32_e32 v20, v53, v53
	v_add_f32_e32 v0, v19, v0
	v_add_f32_e32 v0, v20, v0
	ds_bpermute_b32 v18, v102, v0
	v_ashrrev_i32_e32 v91, 31, v90
	v_mov_b32_e32 v81, v1
	v_mov_b32_e32 v83, v1
	v_mov_b32_e32 v85, v1
	s_waitcnt lgkmcnt(0)
	v_add_f32_e32 v0, v0, v18
	ds_bpermute_b32 v18, v103, v0
	s_waitcnt lgkmcnt(0)
	v_add_f32_e32 v0, v0, v18
	ds_bpermute_b32 v18, v104, v0
	s_waitcnt lgkmcnt(0)
	v_add_f32_e32 v0, v0, v18
	ds_bpermute_b32 v18, v105, v0
	s_waitcnt lgkmcnt(0)
	v_add_f32_e32 v0, v0, v18
	ds_bpermute_b32 v18, v106, v0
	s_waitcnt lgkmcnt(0)
	v_add_f32_e32 v0, v0, v18
	ds_bpermute_b32 v18, v107, v0
	s_waitcnt lgkmcnt(0)
	v_add_f32_e32 v0, v0, v18
	v_fmamk_f32 v0, v0, 0x3a800000, v218
	v_mul_f32_e32 v18, 0x4b800000, v0
	v_cmp_gt_f32_e32 vcc, s13, v0
	s_waitcnt lgkmcnt(0)
	v_pk_add_f32 v[8:9], v[8:9], 1.0 op_sel_hi:[1,0]
	v_cndmask_b32_e32 v0, v0, v18, vcc
	v_rsq_f32_e32 v0, v0
	v_pk_add_f32 v[6:7], v[6:7], 1.0 op_sel_hi:[1,0]
	v_lshlrev_b64 v[18:19], 11, v[90:91]
	v_lshl_add_u64 v[18:19], v[74:75], 0, v[18:19]
	v_mul_f32_e32 v20, 0x45800000, v0
	v_cndmask_b32_e32 v0, v0, v20, vcc
	v_pk_mul_f32 v[20:21], v[64:65], v[0:1] op_sel_hi:[1,0]
	v_pk_mul_f32 v[22:23], v[62:63], v[0:1] op_sel_hi:[1,0]
	v_pk_mul_f32 v[4:5], v[4:5], v[20:21]
	v_pk_mul_f32 v[2:3], v[2:3], v[22:23]
	s_waitcnt lgkmcnt(0)
	v_pk_fma_f32 v[4:5], v[8:9], v[4:5], v[12:13]
	v_pk_fma_f32 v[2:3], v[6:7], v[2:3], v[10:11]
	v_lshl_add_u64 v[6:7], v[14:15], 0, v[80:81]
	v_cvt_pk_bf16_f32 v2, v2, v3
	v_cvt_pk_bf16_f32 v3, v4, v5
	global_store_dwordx2 v[18:19], v[2:3], off
	v_pk_mul_f32 v[20:21], v[60:61], v[0:1] op_sel_hi:[1,0]
	v_pk_mul_f32 v[22:23], v[58:59], v[0:1] op_sel_hi:[1,0]
	s_waitcnt lgkmcnt(0)
	v_pk_add_f32 v[8:9], v[174:175], 1.0 op_sel_hi:[1, 0]
	v_pk_mul_f32 v[2:3], v[168:169], v[22:23]
	v_pk_mul_f32 v[4:5], v[170:171], v[20:21]
	v_pk_add_f32 v[6:7], v[172:173], 1.0 op_sel_hi:[1, 0]
	v_pk_fma_f32 v[4:5], v[8:9], v[4:5], v[178:179]
	v_pk_fma_f32 v[2:3], v[6:7], v[2:3], v[176:177]
	v_lshl_add_u64 v[6:7], v[14:15], 0, v[82:83]
	v_cvt_pk_bf16_f32 v2, v2, v3
	v_cvt_pk_bf16_f32 v3, v4, v5
	global_store_dwordx2 v[18:19], v[2:3], off offset:512
	v_pk_mul_f32 v[20:21], v[56:57], v[0:1] op_sel_hi:[1,0]
	v_pk_mul_f32 v[22:23], v[54:55], v[0:1] op_sel_hi:[1,0]
	s_waitcnt lgkmcnt(0)
	v_pk_add_f32 v[8:9], v[186:187], 1.0 op_sel_hi:[1, 0]
	v_pk_mul_f32 v[2:3], v[180:181], v[22:23]
	v_pk_mul_f32 v[4:5], v[182:183], v[20:21]
	v_pk_add_f32 v[6:7], v[184:185], 1.0 op_sel_hi:[1, 0]
	v_pk_fma_f32 v[4:5], v[8:9], v[4:5], v[190:191]
	v_pk_fma_f32 v[2:3], v[6:7], v[2:3], v[188:189]
	v_lshl_add_u64 v[6:7], v[14:15], 0, v[84:85]
	v_cvt_pk_bf16_f32 v2, v2, v3
	v_cvt_pk_bf16_f32 v3, v4, v5
	global_store_dwordx2 v[18:19], v[2:3], off offset:1024
	v_pk_mul_f32 v[14:15], v[52:53], v[0:1] op_sel_hi:[1,0]
	v_pk_mul_f32 v[16:17], v[50:51], v[0:1] op_sel_hi:[1,0]
	s_waitcnt lgkmcnt(0)
	v_pk_add_f32 v[8:9], v[198:199], 1.0 op_sel_hi:[1, 0]
	v_pk_mul_f32 v[2:3], v[16:17], v[192:193]
	v_pk_mul_f32 v[4:5], v[14:15], v[194:195]
	v_pk_add_f32 v[6:7], v[196:197], 1.0 op_sel_hi:[1, 0]
	v_pk_fma_f32 v[4:5], v[4:5], v[8:9], v[202:203]
	v_pk_fma_f32 v[2:3], v[2:3], v[6:7], v[200:201]
	s_nop 0
	v_cvt_pk_bf16_f32 v2, v2, v3
	v_cvt_pk_bf16_f32 v3, v4, v5
	global_store_dwordx2 v[18:19], v[2:3], off offset:1536
	s_branch .LBB0_529
	s_nop 0
	s_nop 0
	s_nop 0
	s_nop 0
	s_nop 0
	s_nop 0
	s_nop 0
	s_nop 0
	s_nop 0
	s_nop 0
	s_nop 0
	s_nop 0
	s_nop 0
	s_nop 0
	s_nop 0
	s_nop 0
	s_nop 0
	s_nop 0
	s_nop 0
	s_nop 0
	s_nop 0
	s_nop 0
	s_nop 0
	s_nop 0
	s_nop 0
	s_nop 0
	s_nop 0
	s_nop 0
	s_nop 0
	s_nop 0
	s_nop 0
	s_nop 0
	s_nop 0
	s_nop 0
	s_nop 0
	s_nop 0
	s_nop 0
	s_nop 0
	s_nop 0
	s_nop 0
	s_nop 0
	s_nop 0
	s_nop 0
	s_nop 0
	s_nop 0
	s_nop 0
	s_nop 0
	s_nop 0
	s_nop 0
	s_nop 0
	s_nop 0
	s_nop 0
